# v35 + row_ffn00: lane-parallel forget-gate logsigmoid, gain vectors staged in LDS, gate biases hoisted, per-trip rstd load, store-drain waits dropped
# speedup vs baseline: 1.0207x; 1.0107x over previous
.LBB0_259:
	s_load_dwordx2 s[16:17], s[14:15], 0x90
	s_load_dwordx2 s[18:19], s[14:15], 0x10
	s_ashr_i32 s47, s1, 6
	s_lshl_b32 s0, s0, 3
	v_and_b32_e32 v189, 63, v188
	s_add_i32 s45, s0, s47
	s_cmpk_gt_i32 s45, 0x1fff
	v_lshlrev_b32_e32 v128, 3, v189
	s_cbranch_scc1 .LBB0_290
	v_lshlrev_b32_e32 v0, 2, v189
	v_mov_b32_e32 v129, 0
	v_xor_b32_e32 v190, 4, v0
	v_xor_b32_e32 v191, 8, v0
	v_xor_b32_e32 v192, 16, v0
	v_xor_b32_e32 v193, 32, v0
	v_xor_b32_e32 v194, 64, v0
	v_xor_b32_e32 v195, 0x80, v0
	s_waitcnt lgkmcnt(0)
	s_add_u32 s68, s16, 0x1e000000
	s_addc_u32 s69, s17, 0
	v_lshlrev_b32_e32 v230, 6, v188
	global_load_dwordx4 v[232:235], v230, s[68:69]
	global_load_dwordx4 v[236:239], v230, s[68:69] offset:16
	global_load_dwordx4 v[240:243], v230, s[68:69] offset:32
	global_load_dwordx4 v[244:247], v230, s[68:69] offset:48
	v_lshlrev_b32_e32 v249, 4, v188
	v_add_u32_e32 v249, 0x1000, v249
	global_load_dwordx4 v[250:253], v249, s[18:19]
	v_lshrrev_b32_e32 v231, 7, v188
	v_lshlrev_b32_e32 v231, 15, v231
	v_and_b32_e32 v248, 1, v188
	v_lshl_or_b32 v231, v248, 14, v231
	v_bfe_u32 v248, v188, 1, 6
	v_lshl_add_u32 v231, v248, 4, v231
	v_add_u32_e32 v231, 0x2100, v231
	s_waitcnt vmcnt(0)
	ds_write_b128 v231, v[232:235]
	ds_write_b128 v231, v[236:239] offset:1024
	ds_write_b128 v231, v[240:243] offset:2048
	ds_write_b128 v231, v[244:247] offset:3072
	v_add_u32_e32 v249, 0x1f000, v249
	ds_write_b128 v249, v[250:253]
	s_waitcnt lgkmcnt(0)
	s_barrier
	v_lshlrev_b32_e32 v230, 4, v189
	v_add_u32_e32 v230, 0x2100, v230
	v_add_u32_e32 v231, 0x10000, v230
	v_and_b32_e32 v232, 3, v229
	v_lshlrev_b32_e32 v232, 2, v232
	v_add_u32_e32 v233, 0x1d800000, v232
	v_lshlrev_b32_e32 v234, 4, v189
	v_add_u32_e32 v235, 0x21000, v234
	v_add_u32_e32 v234, 0x20000, v234
	v_lshl_add_u64 v[130:131], s[16:17], 0, v[128:129]
	s_mov_b64 s[10:11], 0xd800000
	v_lshlrev_b32_e32 v0, 4, v189
	v_mov_b32_e32 v1, v129
	v_lshl_add_u64 v[132:133], v[130:131], 0, s[10:11]
	v_lshl_add_u64 v[2:3], s[18:19], 0, v[0:1]
	s_mov_b64 s[10:11], 0x1000
	v_lshl_add_u64 v[134:135], v[2:3], 0, s[10:11]
	s_mov_b64 s[10:11], 0x5800000
	v_lshlrev_b32_e32 v4, 7, v189
	v_mov_b32_e32 v5, v129
	s_load_dwordx2 s[20:21], s[14:15], 0x40
	s_load_dwordx2 s[0:1], s[14:15], 0x0
	v_lshl_add_u64 v[136:137], v[130:131], 0, s[10:11]
	v_lshl_add_u64 v[4:5], s[16:17], 0, v[4:5]
	s_mov_b64 s[10:11], 0x1e000000
	s_add_u32 s49, s16, 0x5740000
	v_lshl_add_u64 v[138:139], v[4:5], 0, s[10:11]
	s_mov_b64 s[10:11], 0x2000
	s_addc_u32 s51, s17, 0
	v_lshl_add_u64 v[140:141], v[2:3], 0, s[10:11]
	s_mov_b64 s[10:11], 0x1e002000
	s_add_u32 s53, s16, 0x1d800000
	v_lshl_add_u64 v[142:143], v[4:5], 0, s[10:11]
	s_mov_b64 s[10:11], 0x1e002040
	s_addc_u32 s58, s17, 0
	s_lshl_b32 s22, s45, 2
	s_lshl_b32 s24, s90, 5
	v_lshl_add_u64 v[144:145], v[4:5], 0, s[10:11]
	s_mov_b64 s[10:11], 0x1e004000
	s_waitcnt lgkmcnt(0)
	s_cmp_eq_u64 s[0:1], 0
	v_lshl_add_u64 v[146:147], v[4:5], 0, s[10:11]
	s_mov_b64 s[10:11], 0x1e004040
	s_cselect_b64 s[6:7], -1, 0
	s_cmp_lg_u64 s[0:1], 0
	v_lshl_add_u64 v[148:149], v[4:5], 0, s[10:11]
	s_mov_b64 s[10:11], 0x1e006000
	s_cselect_b64 s[8:9], -1, 0
	v_lshl_add_u64 v[150:151], v[4:5], 0, s[10:11]
	s_mov_b64 s[10:11], 0x1e006040
	s_ashr_i32 s23, s22, 31
	s_ashr_i32 s25, s24, 31
	v_lshl_add_u64 v[152:153], v[4:5], 0, s[10:11]
	s_or_b32 s26, s22, 3
	s_lshl_b64 s[28:29], s[22:23], 11
	s_lshl_b64 s[30:31], s[24:25], 11
	s_lshl_b64 s[10:11], s[22:23], 12
	s_add_u32 s0, s0, s10
	s_addc_u32 s1, s1, s11
	v_lshl_add_u64 v[0:1], s[0:1], 0, v[0:1]
	s_mov_b64 s[0:1], 0x3c00
	v_lshl_add_u64 v[154:155], v[0:1], 0, s[0:1]
	v_cndmask_b32_e64 v0, 0, 1, s[8:9]
	v_cmp_eq_u32_e64 s[4:5], 0, v189
	s_mov_b32 s27, s23
	s_lshl_b64 s[34:35], s[24:25], 12
	s_lshl_b64 s[36:37], s[22:23], 2
	s_lshl_b64 s[38:39], s[24:25], 2
	s_lshl_b64 s[40:41], s[22:23], 5
	s_lshl_b64 s[42:43], s[24:25], 5
	v_cmp_ne_u32_e64 s[8:9], 1, v0
	s_mov_b32 s23, 0xd800000
	v_mov_b32_e32 v196, 0x5740000
	v_mov_b32_e32 v197, 0x358637bd
	s_mov_b32 s59, 0x800000
	s_mov_b32 s60, 0x5800000
	s_mov_b32 s61, 0xf800000
	v_mov_b32_e32 v198, 0x260
	s_mov_b32 s62, 0xbfb8aa3b
	s_mov_b32 s63, 0x3f2aaaab
	s_mov_b32 s44, 0x3ecc95a3
	s_mov_b32 s46, 0x3e9b6dac
	s_mov_b32 s48, 0x3f2aaada
	s_mov_b32 s50, 0x3f317218
	s_mov_b32 s52, 0xb102e308
	s_mov_b32 s64, 0x7f800000
	s_mov_b32 s65, 0x33800000
	v_mov_b32_e32 v199, 0x1d800000
	s_mov_b32 s66, 0x5801000
	v_mov_b32_e32 v200, 0x7f800000
	v_mov_b32_e32 v201, 0x7fc00000
	v_mov_b32_e32 v202, 0xff800000
	global_load_dword v236, v232, s[20:21] offset:16
	global_load_dword v237, v232, s[20:21]
	s_waitcnt vmcnt(0)
	s_branch .LBB0_262

.LBB0_266:
	v_lshl_add_u64 v[88:89], v[130:131], 0, s[28:29]
	v_add_co_u32_e32 v64, vcc, s23, v88
	s_nop 1
	v_addc_co_u32_e32 v65, vcc, 0, v89, vcc
	global_load_dwordx2 v[72:73], v[64:65], off nt
	global_load_dwordx2 v[70:71], v[64:65], off offset:512 nt
	global_load_dwordx2 v[68:69], v[64:65], off offset:1024 nt
	global_load_dwordx2 v[66:67], v[64:65], off offset:1536 nt
	global_load_dwordx2 v[104:105], v[64:65], off offset:2048 nt
	global_load_dwordx2 v[102:103], v[64:65], off offset:2560 nt
	global_load_dwordx2 v[100:101], v[64:65], off offset:3072 nt
	global_load_dwordx2 v[98:99], v[64:65], off offset:3584 nt
	v_add_co_u32_e32 v64, vcc, 0xd801000, v88
	s_nop 1
	v_addc_co_u32_e32 v65, vcc, 0, v89, vcc
	global_load_dwordx2 v[96:97], v[64:65], off nt
	global_load_dwordx2 v[94:95], v[64:65], off offset:512 nt
	global_load_dwordx2 v[92:93], v[64:65], off offset:1024 nt
	global_load_dwordx2 v[90:91], v[64:65], off offset:1536 nt
	v_lshl_add_u64 v[64:65], v[132:133], 0, s[0:1]
	global_load_dwordx2 v[86:87], v[64:65], off nt
	global_load_dwordx2 v[84:85], v[64:65], off offset:512 nt
	global_load_dwordx2 v[82:83], v[64:65], off offset:1024 nt
	global_load_dwordx2 v[80:81], v[64:65], off offset:1536 nt
	v_cndmask_b32_e64 v64, 0, 1, s[6:7]
	v_cmp_ne_u32_e64 s[10:11], 1, v64
	s_andn2_b64 vcc, exec, s[6:7]
	v_mov_b32_e32 v238, 1.0
	v_mov_b32_e32 v239, 1.0
	v_mov_b32_e32 v240, 1.0
	v_mov_b32_e32 v241, 1.0
	s_cbranch_vccnz .LBB0_268
	s_add_u32 s12, s16, s36
	s_addc_u32 s13, s17, s37
	global_load_dwordx4 v[238:241], v196, s[12:13]
.LBB0_268:
	s_waitcnt vmcnt(0)
	v_mov_b32_e32 v64, v238
	v_and_b32_e32 v125, 0xffff0000, v71
	v_and_b32_e32 v124, 0xffff0000, v70
	v_lshlrev_b32_e32 v120, 16, v72
	v_and_b32_e32 v121, 0xffff0000, v72
	v_lshlrev_b32_e32 v72, 16, v73
	v_and_b32_e32 v73, 0xffff0000, v73
	v_lshlrev_b32_e32 v123, 16, v71
	v_lshlrev_b32_e32 v122, 16, v70
	v_pk_mul_f32 v[70:71], v[124:125], v[124:125]
	v_mul_f32_e32 v106, v73, v73
	v_pk_fma_f32 v[126:127], v[122:123], v[122:123], v[70:71]
	v_lshlrev_b32_e32 v204, 16, v68
	v_and_b32_e32 v205, 0xffff0000, v68
	v_lshlrev_b32_e32 v206, 16, v69
	v_and_b32_e32 v207, 0xffff0000, v69
	ds_read_b128 v[68:71], v234
	v_lshlrev_b32_e32 v209, 16, v66
	v_and_b32_e32 v211, 0xffff0000, v66
	v_mul_f32_e32 v66, v121, v121
	v_pk_fma_f32 v[114:115], v[72:73], v[72:73], v[106:107] op_sel_hi:[1,1,0]
	v_lshlrev_b32_e32 v212, 16, v67
	v_and_b32_e32 v213, 0xffff0000, v67
	v_pk_fma_f32 v[66:67], v[120:121], v[120:121], v[66:67] op_sel_hi:[1,1,0]
	ds_read_b128 v[106:109], v234 offset:1024
	ds_read_b128 v[110:113], v234 offset:2048
	v_mov_b32_e32 v208, v66
	v_mov_b32_e32 v214, v114
	v_pk_add_f32 v[66:67], v[66:67], v[114:115]
	ds_read_b128 v[114:117], v234 offset:3072
	s_waitcnt lgkmcnt(0)
	v_lshlrev_b32_e32 v74, 16, v170
	v_and_b32_e32 v75, 0xffff0000, v170
	v_lshlrev_b32_e32 v76, 16, v171
	v_and_b32_e32 v77, 0xffff0000, v171
	v_mov_b32_e32 v215, v209
	v_pk_mul_f32 v[76:77], v[64:65], v[76:77] op_sel_hi:[0,1]
	v_pk_mul_f32 v[74:75], v[64:65], v[74:75] op_sel_hi:[0,1]
	v_mul_f32_e32 v65, v211, v211
	v_pk_mul_f32 v[214:215], v[208:209], v[214:215]
	v_pk_add_f32 v[126:127], v[126:127], v[126:127] op_sel:[0,1] op_sel_hi:[1,0]
	v_mov_b32_e32 v67, v215
	v_mov_b32_e32 v127, v65
	v_pk_add_f32 v[66:67], v[66:67], v[126:127]
	v_mul_f32_e32 v126, v205, v205
	v_mul_f32_e32 v208, v207, v207
	v_mul_f32_e32 v119, v212, v212
	v_mul_f32_e32 v203, v213, v213
	v_pk_fma_f32 v[126:127], v[204:205], v[204:205], v[126:127] op_sel_hi:[1,1,0]
	v_pk_fma_f32 v[214:215], v[206:207], v[206:207], v[208:209] op_sel_hi:[1,1,0]
	v_mov_b32_e32 v127, v119
	v_mov_b32_e32 v215, v203
	v_pk_add_f32 v[126:127], v[126:127], v[214:215]
	v_cndmask_b32_e64 v79, v1, v75, s[6:7]
	v_pk_add_f32 v[66:67], v[66:67], v[126:127]
	v_cndmask_b32_e64 v78, v0, v74, s[6:7]
	v_add_f32_e32 v65, v66, v67
	ds_bpermute_b32 v126, v190, v65
	v_cndmask_b32_e64 v75, v3, v77, s[6:7]
	v_cndmask_b32_e64 v74, v2, v76, s[6:7]
	v_lshlrev_b32_e32 v76, 16, v168
	v_and_b32_e32 v77, 0xffff0000, v168
	v_lshlrev_b32_e32 v118, 16, v169
	v_and_b32_e32 v119, 0xffff0000, v169
	v_pk_mul_f32 v[66:67], v[64:65], v[118:119] op_sel_hi:[0,1]
	v_pk_mul_f32 v[76:77], v[64:65], v[76:77] op_sel_hi:[0,1]
	s_waitcnt lgkmcnt(0)
	v_add_f32_e32 v65, v65, v126
	v_cndmask_b32_e64 v119, v5, v77, s[6:7]
	ds_bpermute_b32 v77, v191, v65
	v_lshlrev_b32_e32 v126, 16, v167
	v_and_b32_e32 v127, 0xffff0000, v167
	v_cndmask_b32_e64 v118, v4, v76, s[6:7]
	v_lshlrev_b32_e32 v76, 16, v166
	s_waitcnt lgkmcnt(0)
	v_add_f32_e32 v65, v65, v77
	ds_bpermute_b32 v203, v192, v65
	v_pk_mul_f32 v[126:127], v[64:65], v[126:127] op_sel_hi:[0,1]
	v_and_b32_e32 v77, 0xffff0000, v166
	v_lshlrev_b32_e32 v216, 16, v165
	v_and_b32_e32 v217, 0xffff0000, v165
	s_waitcnt lgkmcnt(0)
	v_add_f32_e32 v65, v65, v203
	ds_bpermute_b32 v203, v193, v65
	v_pk_mul_f32 v[76:77], v[64:65], v[76:77] op_sel_hi:[0,1]
	v_cndmask_b32_e64 v215, v9, v77, s[6:7]
	v_cndmask_b32_e64 v214, v8, v76, s[6:7]
	v_lshlrev_b32_e32 v76, 16, v164
	s_waitcnt lgkmcnt(0)
	v_add_f32_e32 v65, v65, v203
	ds_bpermute_b32 v203, v194, v65
	v_and_b32_e32 v77, 0xffff0000, v164
	v_pk_mul_f32 v[216:217], v[64:65], v[216:217] op_sel_hi:[0,1]
	v_cndmask_b32_e64 v67, v7, v67, s[6:7]
	v_cndmask_b32_e64 v66, v6, v66, s[6:7]
	s_waitcnt lgkmcnt(0)
	v_add_f32_e32 v203, v65, v203
	ds_bpermute_b32 v208, v195, v203
	v_pk_mul_f32 v[64:65], v[64:65], v[76:77] op_sel_hi:[0,1]
	v_cndmask_b32_e64 v219, v13, v65, s[6:7]
	v_cndmask_b32_e64 v218, v12, v64, s[6:7]
	v_cndmask_b32_e64 v217, v15, v217, s[6:7]
	s_waitcnt lgkmcnt(0)
	v_add_f32_e32 v65, v203, v208
	v_fmamk_f32 v65, v65, 0x3a800000, v197
	v_mul_f32_e32 v76, 0x4b800000, v65
	v_cmp_gt_f32_e32 vcc, s59, v65
	v_cndmask_b32_e64 v216, v14, v216, s[6:7]
	v_cndmask_b32_e64 v127, v11, v127, s[6:7]
	v_cndmask_b32_e32 v65, v65, v76, vcc
	v_rsq_f32_e32 v65, v65
	v_cndmask_b32_e64 v126, v10, v126, s[6:7]
	v_mov_b32_e32 v210, v209
	v_mul_f32_e32 v64, 0x45800000, v65
	v_cndmask_b32_e32 v64, v65, v64, vcc
	v_mul_f32_e32 v208, 0.5, v64
	v_pk_mul_f32 v[64:65], v[208:209], v[120:121] op_sel_hi:[0,1]
	v_pk_mul_f32 v[72:73], v[208:209], v[72:73] op_sel_hi:[0,1]
	s_waitcnt lgkmcnt(9)
	v_pk_fma_f32 v[76:77], v[68:69], v[64:65], v[78:79]
	v_mov_b32_e32 v64, v122
	v_mov_b32_e32 v65, v124
	v_mov_b32_e32 v124, v123
	v_pk_fma_f32 v[74:75], v[70:71], v[72:73], v[74:75]
	v_pk_mul_f32 v[64:65], v[208:209], v[64:65] op_sel_hi:[0,1]
	v_pk_mul_f32 v[68:69], v[208:209], v[124:125] op_sel_hi:[0,1]
	v_pk_mul_f32 v[78:79], v[212:213], v[208:209] op_sel_hi:[1,0]
	s_waitcnt lgkmcnt(8)
	v_pk_fma_f32 v[70:71], v[108:109], v[68:69], v[66:67]
	v_pk_fma_f32 v[72:73], v[106:107], v[64:65], v[118:119]
	v_pk_mul_f32 v[66:67], v[208:209], v[204:205] op_sel_hi:[0,1]
	s_waitcnt lgkmcnt(6)
	v_pk_fma_f32 v[108:109], v[116:117], v[78:79], v[216:217]
	v_pk_mul_f32 v[78:79], v[74:75], v[74:75]
	v_pk_mul_f32 v[106:107], v[76:77], v[76:77]
	v_pk_fma_f32 v[66:67], v[110:111], v[66:67], v[214:215]
	v_pk_mov_b32 v[110:111], v[106:107], v[78:79] op_sel:[1,0]
	v_mov_b32_e32 v107, v79
	v_pk_add_f32 v[78:79], v[110:111], v[106:107]
	v_pk_mul_f32 v[64:65], v[208:209], v[206:207] op_sel_hi:[0,1]
	v_pk_add_f32 v[78:79], v[78:79], v[78:79] op_sel_hi:[0,1]
	v_pk_mul_f32 v[106:107], v[70:71], v[70:71]
	v_pk_mul_f32 v[110:111], v[72:73], v[72:73]
	v_pk_fma_f32 v[64:65], v[112:113], v[64:65], v[126:127]
	v_pk_mov_b32 v[112:113], v[110:111], v[106:107] op_sel:[1,0]
	v_mov_b32_e32 v111, v107
	v_mul_f32_e32 v78, v66, v66
	v_pk_mul_f32 v[68:69], v[210:211], v[208:209] op_sel_hi:[1,0]
	v_pk_add_f32 v[106:107], v[112:113], v[110:111]
	v_pk_fma_f32 v[110:111], v[66:67], v[66:67], v[78:79] op_sel_hi:[1,1,0]
	v_mul_f32_e32 v78, v64, v64
	v_pk_fma_f32 v[68:69], v[114:115], v[68:69], v[218:219]
	v_pk_add_f32 v[106:107], v[106:107], v[106:107] op_sel_hi:[0,1]
	v_pk_fma_f32 v[112:113], v[64:65], v[64:65], v[78:79] op_sel_hi:[1,1,0]
	v_mul_f32_e32 v110, v68, v68
	v_mul_f32_e32 v112, v69, v69
	v_mul_f32_e32 v78, v108, v108
	v_mul_f32_e32 v106, v109, v109
	v_pk_add_f32 v[110:111], v[110:111], v[112:113]
	v_pk_add_f32 v[78:79], v[78:79], v[106:107]
	s_nop 0
	v_pk_add_f32 v[78:79], v[110:111], v[78:79]
	s_nop 0
	v_add_f32_e32 v78, v78, v79
	ds_bpermute_b32 v79, v190, v78
	s_waitcnt lgkmcnt(0)
	v_add_f32_e32 v78, v78, v79
	ds_bpermute_b32 v79, v191, v78
	s_waitcnt lgkmcnt(0)
	v_add_f32_e32 v78, v78, v79
	ds_bpermute_b32 v79, v192, v78
	s_waitcnt lgkmcnt(0)
	v_add_f32_e32 v78, v78, v79
	ds_bpermute_b32 v79, v193, v78
	s_waitcnt lgkmcnt(0)
	v_add_f32_e32 v78, v78, v79
	ds_bpermute_b32 v79, v194, v78
	s_waitcnt lgkmcnt(0)
	v_add_f32_e32 v78, v78, v79
	ds_bpermute_b32 v79, v195, v78
	s_waitcnt lgkmcnt(0)
	v_add_f32_e32 v78, v78, v79
	v_fmamk_f32 v78, v78, 0x3a800000, v197
	v_mul_f32_e32 v79, 0x4b800000, v78
	v_cmp_gt_f32_e32 vcc, s59, v78
	s_nop 1
	v_cndmask_b32_e32 v79, v78, v79, vcc
	v_rsq_f32_e32 v79, v79
	s_nop 0
	v_mul_f32_e32 v106, 0x45800000, v79
	v_cndmask_b32_e32 v110, v79, v106, vcc
	v_pk_mul_f32 v[106:107], v[74:75], v[110:111] op_sel_hi:[1,0]
	v_pk_mul_f32 v[112:113], v[76:77], v[110:111] op_sel_hi:[1,0]
	v_pk_mul_f32 v[114:115], v[72:73], v[110:111] op_sel_hi:[1,0]
	v_cvt_pk_bf16_f32 v112, v112, v113
	v_cvt_pk_bf16_f32 v113, v106, v107
	v_add_co_u32_e32 v106, vcc, s60, v88
	v_cvt_pk_bf16_f32 v114, v114, v115
	s_nop 0
	v_addc_co_u32_e32 v107, vcc, 0, v89, vcc
	global_store_dwordx2 v[106:107], v[112:113], off
	v_pk_mul_f32 v[112:113], v[70:71], v[110:111] op_sel_hi:[1,0]
	s_nop 0
	v_cvt_pk_bf16_f32 v115, v112, v113
	global_store_dwordx2 v[106:107], v[114:115], off offset:512
	v_pk_mul_f32 v[112:113], v[64:65], v[110:111] op_sel_hi:[1,0]
	v_pk_mul_f32 v[114:115], v[66:67], v[110:111] op_sel_hi:[1,0]
	s_nop 0
	v_cvt_pk_bf16_f32 v114, v114, v115
	v_cvt_pk_bf16_f32 v115, v112, v113
	global_store_dwordx2 v[106:107], v[114:115], off offset:1024
	v_pk_mul_f32 v[112:113], v[108:109], v[110:111] op_sel_hi:[1,0]
	v_pk_mul_f32 v[114:115], v[68:69], v[110:111] op_sel_hi:[1,0]
	s_nop 0
	v_cvt_pk_bf16_f32 v114, v114, v115
	v_cvt_pk_bf16_f32 v115, v112, v113
	global_store_dwordx2 v[106:107], v[114:115], off offset:1536
	s_and_saveexec_b64 s[56:57], s[4:5]
	s_cbranch_execz .LBB0_270
	v_mul_f32_e32 v79, 0x4f800000, v78
	v_cmp_gt_f32_e32 vcc, s61, v78
	s_nop 1
	v_cndmask_b32_e32 v78, v78, v79, vcc
	v_sqrt_f32_e32 v79, v78
	s_nop 0
	v_add_u32_e32 v111, -1, v79
	v_fma_f32 v113, -v111, v79, v78
	v_add_u32_e32 v112, 1, v79
	v_cmp_ge_f32_e64 s[12:13], 0, v113
	s_nop 1
	v_cndmask_b32_e64 v111, v79, v111, s[12:13]
	v_fma_f32 v79, -v112, v79, v78
	v_cmp_lt_f32_e64 s[12:13], 0, v79
	s_nop 1
	v_cndmask_b32_e64 v79, v111, v112, s[12:13]
	v_mul_f32_e32 v111, 0x37800000, v79
	v_cndmask_b32_e32 v79, v79, v111, vcc
	v_cmp_class_f32_e32 vcc, v78, v198
	s_add_u32 s12, s16, s36
	s_addc_u32 s13, s17, s37
	v_cndmask_b32_e32 v78, v79, v78, vcc
	global_store_dword v196, v78, s[12:13]
.LBB0_270:
	s_or_b64 exec, exec, s[56:57]
	ds_read_b128 v[112:115], v235
	ds_read_b128 v[116:119], v230 offset:3072
	ds_read_b128 v[120:123], v230 offset:2048
	ds_read_b128 v[124:127], v230 offset:1024
	ds_read_b128 v[204:207], v230
	v_mul_f32_e32 v76, v76, v110
	v_mul_f32_e32 v74, v74, v110
	v_mul_f32_e32 v72, v72, v110
	v_mul_f32_e32 v70, v70, v110
	v_mul_f32_e32 v66, v66, v110
	v_mul_f32_e32 v64, v64, v110
	v_mul_f32_e32 v68, v68, v110
	v_mul_f32_e32 v108, v108, v110
	s_waitcnt lgkmcnt(4)
	v_mul_f32_e32 v76, v76, v112
	v_mul_f32_e32 v74, v74, v114
	s_waitcnt lgkmcnt(1)
	v_pk_fma_f32 v[126:127], v[126:127], v[76:77], 0 op_sel_hi:[1,0,0]
	s_waitcnt lgkmcnt(0)
	v_pk_fma_f32 v[78:79], v[206:207], v[76:77], 0 op_sel_hi:[1,0,0]
	v_pk_fma_f32 v[204:205], v[204:205], v[76:77], 0 op_sel_hi:[1,0,0]
	v_pk_fma_f32 v[124:125], v[124:125], v[76:77], 0 op_sel_hi:[1,0,0]
	v_mul_f32_e32 v76, v77, v110
	v_mul_f32_e32 v76, v76, v113
	v_pk_fma_f32 v[112:113], v[122:123], v[76:77], v[78:79] op_sel_hi:[1,0,1]
	v_pk_fma_f32 v[204:205], v[120:121], v[76:77], v[204:205] op_sel_hi:[1,0,1]
	v_pk_fma_f32 v[206:207], v[76:77], v[118:119], v[126:127] op_sel_hi:[0,1,1]
	v_pk_fma_f32 v[208:209], v[76:77], v[116:117], v[124:125] op_sel_hi:[0,1,1]
	ds_read_b128 v[76:79], v230 offset:19456
	ds_read_b128 v[116:119], v230 offset:18432
	ds_read_b128 v[120:123], v230 offset:17408
	ds_read_b128 v[124:127], v230 offset:16384
	s_waitcnt lgkmcnt(1)
	v_pk_fma_f32 v[120:121], v[74:75], v[120:121], v[208:209] op_sel_hi:[0,1,1]
	s_waitcnt lgkmcnt(0)
	v_pk_fma_f32 v[124:125], v[74:75], v[124:125], v[204:205] op_sel_hi:[0,1,1]
	v_pk_fma_f32 v[112:113], v[74:75], v[126:127], v[112:113] op_sel_hi:[0,1,1]
	v_pk_fma_f32 v[122:123], v[74:75], v[122:123], v[206:207] op_sel_hi:[0,1,1]
	v_mul_f32_e32 v74, v75, v110
	v_mul_f32_e32 v74, v74, v115
	v_pk_fma_f32 v[204:205], v[74:75], v[118:119], v[112:113] op_sel_hi:[0,1,1]
	v_pk_fma_f32 v[206:207], v[74:75], v[116:117], v[124:125] op_sel_hi:[0,1,1]
	v_pk_fma_f32 v[78:79], v[74:75], v[78:79], v[122:123] op_sel_hi:[0,1,1]
	v_pk_fma_f32 v[208:209], v[74:75], v[76:77], v[120:121] op_sel_hi:[0,1,1]
	ds_read_b128 v[74:77], v235 offset:1024
	ds_read_b128 v[112:115], v230 offset:35840
	ds_read_b128 v[116:119], v230 offset:34816
	ds_read_b128 v[120:123], v230 offset:33792
	ds_read_b128 v[124:127], v230 offset:32768
	s_waitcnt lgkmcnt(4)
	v_mul_f32_e32 v72, v72, v74
	v_mul_f32_e32 v70, v70, v76
	s_waitcnt lgkmcnt(1)
	v_pk_fma_f32 v[120:121], v[120:121], v[72:73], v[208:209] op_sel_hi:[1,0,1]
	s_waitcnt lgkmcnt(0)
	v_pk_fma_f32 v[124:125], v[124:125], v[72:73], v[206:207] op_sel_hi:[1,0,1]
	v_pk_fma_f32 v[126:127], v[126:127], v[72:73], v[204:205] op_sel_hi:[1,0,1]
	v_pk_fma_f32 v[78:79], v[122:123], v[72:73], v[78:79] op_sel_hi:[1,0,1]
	v_mul_f32_e32 v72, v73, v110
	v_mul_f32_e32 v72, v72, v75
	v_pk_fma_f32 v[126:127], v[118:119], v[72:73], v[126:127] op_sel_hi:[1,0,1]
	v_pk_fma_f32 v[124:125], v[116:117], v[72:73], v[124:125] op_sel_hi:[1,0,1]
	v_pk_fma_f32 v[78:79], v[72:73], v[114:115], v[78:79] op_sel_hi:[0,1,1]
	v_pk_fma_f32 v[204:205], v[72:73], v[112:113], v[120:121] op_sel_hi:[0,1,1]
	ds_read_b128 v[72:75], v230 offset:52224
	ds_read_b128 v[112:115], v230 offset:51200
	ds_read_b128 v[116:119], v230 offset:50176
	ds_read_b128 v[120:123], v230 offset:49152
	s_waitcnt lgkmcnt(1)
	v_pk_fma_f32 v[116:117], v[70:71], v[116:117], v[204:205] op_sel_hi:[0,1,1]
	s_waitcnt lgkmcnt(0)
	v_pk_fma_f32 v[120:121], v[70:71], v[120:121], v[124:125] op_sel_hi:[0,1,1]
	v_pk_fma_f32 v[122:123], v[70:71], v[122:123], v[126:127] op_sel_hi:[0,1,1]
	v_pk_fma_f32 v[78:79], v[70:71], v[118:119], v[78:79] op_sel_hi:[0,1,1]
	v_mul_f32_e32 v70, v71, v110
	v_mul_f32_e32 v70, v70, v77
	v_pk_fma_f32 v[124:125], v[70:71], v[114:115], v[122:123] op_sel_hi:[0,1,1]
	v_pk_fma_f32 v[126:127], v[70:71], v[112:113], v[120:121] op_sel_hi:[0,1,1]
	v_pk_fma_f32 v[78:79], v[70:71], v[74:75], v[78:79] op_sel_hi:[0,1,1]
	v_pk_fma_f32 v[204:205], v[70:71], v[72:73], v[116:117] op_sel_hi:[0,1,1]
	ds_read_b128 v[70:73], v235 offset:2048
	ds_read_b128 v[74:77], v231 offset:3072
	ds_read_b128 v[112:115], v231 offset:2048
	ds_read_b128 v[116:119], v231 offset:1024
	ds_read_b128 v[120:123], v231
	s_waitcnt lgkmcnt(4)
	v_mul_f32_e32 v66, v66, v70
	v_mul_f32_e32 v64, v64, v72
	s_waitcnt lgkmcnt(1)
	v_pk_fma_f32 v[116:117], v[116:117], v[66:67], v[204:205] op_sel_hi:[1,0,1]
	s_waitcnt lgkmcnt(0)
	v_pk_fma_f32 v[120:121], v[120:121], v[66:67], v[126:127] op_sel_hi:[1,0,1]
	v_pk_fma_f32 v[122:123], v[122:123], v[66:67], v[124:125] op_sel_hi:[1,0,1]
	v_pk_fma_f32 v[78:79], v[118:119], v[66:67], v[78:79] op_sel_hi:[1,0,1]
	v_mul_f32_e32 v66, v67, v110
	v_mul_f32_e32 v66, v66, v71
	v_pk_fma_f32 v[70:71], v[114:115], v[66:67], v[122:123] op_sel_hi:[1,0,1]
	v_pk_fma_f32 v[124:125], v[112:113], v[66:67], v[120:121] op_sel_hi:[1,0,1]
	v_pk_fma_f32 v[78:79], v[66:67], v[76:77], v[78:79] op_sel_hi:[0,1,1]
	v_pk_fma_f32 v[66:67], v[66:67], v[74:75], v[116:117] op_sel_hi:[0,1,1]
	ds_read_b128 v[74:77], v231 offset:19456
	ds_read_b128 v[112:115], v231 offset:18432
	ds_read_b128 v[116:119], v231 offset:17408
	ds_read_b128 v[120:123], v231 offset:16384
	s_waitcnt lgkmcnt(1)
	v_pk_fma_f32 v[66:67], v[64:65], v[116:117], v[66:67] op_sel_hi:[0,1,1]
	s_waitcnt lgkmcnt(0)
	v_pk_fma_f32 v[120:121], v[64:65], v[120:121], v[124:125] op_sel_hi:[0,1,1]
	v_pk_fma_f32 v[70:71], v[64:65], v[122:123], v[70:71] op_sel_hi:[0,1,1]
	v_pk_fma_f32 v[78:79], v[64:65], v[118:119], v[78:79] op_sel_hi:[0,1,1]
	v_mul_f32_e32 v64, v65, v110
	v_mul_f32_e32 v64, v64, v73
	v_pk_fma_f32 v[122:123], v[64:65], v[114:115], v[70:71] op_sel_hi:[0,1,1]
	v_pk_fma_f32 v[120:121], v[64:65], v[112:113], v[120:121] op_sel_hi:[0,1,1]
	v_pk_fma_f32 v[78:79], v[64:65], v[76:77], v[78:79] op_sel_hi:[0,1,1]
	v_pk_fma_f32 v[124:125], v[64:65], v[74:75], v[66:67] op_sel_hi:[0,1,1]
	ds_read_b128 v[64:67], v235 offset:3072
	ds_read_b128 v[70:73], v231 offset:35840
	ds_read_b128 v[74:77], v231 offset:34816
	ds_read_b128 v[112:115], v231 offset:33792
	ds_read_b128 v[116:119], v231 offset:32768
	s_waitcnt lgkmcnt(4)
	v_mul_f32_e32 v64, v68, v64
	v_mul_f32_e32 v66, v108, v66
	s_waitcnt lgkmcnt(1)
	v_pk_fma_f32 v[112:113], v[112:113], v[64:65], v[124:125] op_sel_hi:[1,0,1]
	s_waitcnt lgkmcnt(0)
	v_pk_fma_f32 v[116:117], v[116:117], v[64:65], v[120:121] op_sel_hi:[1,0,1]
	v_pk_fma_f32 v[118:119], v[118:119], v[64:65], v[122:123] op_sel_hi:[1,0,1]
	v_pk_fma_f32 v[78:79], v[114:115], v[64:65], v[78:79] op_sel_hi:[1,0,1]
	v_mul_f32_e32 v64, v69, v110
	v_mul_f32_e32 v68, v64, v65
	v_pk_fma_f32 v[114:115], v[76:77], v[68:69], v[118:119] op_sel_hi:[1,0,1]
	v_pk_fma_f32 v[116:117], v[74:75], v[68:69], v[116:117] op_sel_hi:[1,0,1]
	v_pk_fma_f32 v[64:65], v[68:69], v[72:73], v[78:79] op_sel_hi:[0,1,1]
	v_pk_fma_f32 v[112:113], v[68:69], v[70:71], v[112:113] op_sel_hi:[0,1,1]
	ds_read_b128 v[68:71], v231 offset:52224
	ds_read_b128 v[72:75], v231 offset:51200
	ds_read_b128 v[76:79], v231 offset:50176
	ds_read_b128 v[118:121], v231 offset:49152
	s_waitcnt lgkmcnt(1)
	v_pk_fma_f32 v[76:77], v[66:67], v[76:77], v[112:113] op_sel_hi:[0,1,1]
	s_waitcnt lgkmcnt(0)
	v_pk_fma_f32 v[116:117], v[66:67], v[118:119], v[116:117] op_sel_hi:[0,1,1]
	v_pk_fma_f32 v[114:115], v[66:67], v[120:121], v[114:115] op_sel_hi:[0,1,1]
	v_pk_fma_f32 v[64:65], v[66:67], v[78:79], v[64:65] op_sel_hi:[0,1,1]
	v_mul_f32_e32 v66, v109, v110
	v_mul_f32_e32 v78, v66, v67
	v_pk_fma_f32 v[64:65], v[78:79], v[70:71], v[64:65] op_sel_hi:[0,1,1]
	v_pk_fma_f32 v[70:71], v[78:79], v[68:69], v[76:77] op_sel_hi:[0,1,1]
	ds_bpermute_b32 v77, v190, v64
	ds_bpermute_b32 v68, v190, v70
	v_pk_fma_f32 v[66:67], v[78:79], v[74:75], v[114:115] op_sel_hi:[0,1,1]
	v_pk_fma_f32 v[72:73], v[78:79], v[72:73], v[116:117] op_sel_hi:[0,1,1]
	ds_bpermute_b32 v74, v190, v72
	s_waitcnt lgkmcnt(2)
	v_add_f32_e32 v64, v64, v77
	ds_bpermute_b32 v77, v191, v64
	s_waitcnt lgkmcnt(2)
	v_add_f32_e32 v68, v70, v68
	ds_bpermute_b32 v75, v190, v73
	ds_bpermute_b32 v70, v190, v71
	ds_bpermute_b32 v76, v190, v66
	s_waitcnt lgkmcnt(3)
	v_add_f32_e32 v64, v64, v77
	ds_bpermute_b32 v77, v192, v64
	s_waitcnt lgkmcnt(3)
	v_pk_add_f32 v[72:73], v[72:73], v[74:75]
	s_waitcnt lgkmcnt(2)
	v_add_f32_e32 v70, v71, v70
	ds_bpermute_b32 v69, v191, v68
	ds_bpermute_b32 v74, v191, v72
	s_waitcnt lgkmcnt(2)
	v_add_f32_e32 v64, v64, v77
	ds_bpermute_b32 v77, v193, v64
	ds_bpermute_b32 v75, v191, v73
	ds_bpermute_b32 v71, v191, v70
	s_waitcnt lgkmcnt(4)
	v_add_f32_e32 v68, v68, v69
	ds_bpermute_b32 v69, v192, v68
	s_waitcnt lgkmcnt(3)
	v_add_f32_e32 v64, v64, v77
	ds_bpermute_b32 v77, v194, v64
	s_waitcnt lgkmcnt(3)
	v_pk_add_f32 v[72:73], v[72:73], v[74:75]
	s_waitcnt lgkmcnt(2)
	v_add_f32_e32 v70, v70, v71
	ds_bpermute_b32 v74, v192, v72
	ds_bpermute_b32 v75, v192, v73
	s_waitcnt lgkmcnt(2)
	v_add_f32_e32 v108, v64, v77
	ds_bpermute_b32 v77, v190, v67
	ds_bpermute_b32 v64, v190, v65
	ds_bpermute_b32 v71, v192, v70
	v_add_f32_e32 v68, v68, v69
	s_waitcnt lgkmcnt(3)
	v_pk_add_f32 v[72:73], v[72:73], v[74:75]
	s_waitcnt lgkmcnt(2)
	v_pk_add_f32 v[66:67], v[66:67], v[76:77]
	s_waitcnt lgkmcnt(1)
	v_add_f32_e32 v64, v65, v64
	ds_bpermute_b32 v76, v191, v66
	ds_bpermute_b32 v77, v191, v67
	ds_bpermute_b32 v65, v191, v64
	s_waitcnt lgkmcnt(3)
	v_add_f32_e32 v70, v70, v71
	ds_bpermute_b32 v69, v193, v68
	ds_bpermute_b32 v74, v193, v72
	s_waitcnt lgkmcnt(3)
	v_pk_add_f32 v[66:67], v[66:67], v[76:77]
	s_waitcnt lgkmcnt(2)
	v_add_f32_e32 v64, v64, v65
	ds_bpermute_b32 v76, v192, v66
	ds_bpermute_b32 v77, v192, v67
	ds_bpermute_b32 v65, v192, v64
	ds_bpermute_b32 v75, v193, v73
	ds_bpermute_b32 v71, v193, v70
	s_waitcnt lgkmcnt(6)
	v_add_f32_e32 v68, v68, v69
	s_waitcnt lgkmcnt(3)
	v_pk_add_f32 v[66:67], v[66:67], v[76:77]
	s_waitcnt lgkmcnt(2)
	v_add_f32_e32 v64, v64, v65
	ds_bpermute_b32 v76, v193, v66
	ds_bpermute_b32 v77, v193, v67
	ds_bpermute_b32 v65, v193, v64
	s_waitcnt lgkmcnt(4)
	v_pk_add_f32 v[72:73], v[72:73], v[74:75]
	s_waitcnt lgkmcnt(3)
	v_add_f32_e32 v70, v70, v71
	ds_bpermute_b32 v69, v194, v68
	s_waitcnt lgkmcnt(2)
	v_pk_add_f32 v[66:67], v[66:67], v[76:77]
	s_waitcnt lgkmcnt(1)
	v_add_f32_e32 v64, v64, v65
	ds_bpermute_b32 v74, v194, v72
	ds_bpermute_b32 v75, v194, v73
	ds_bpermute_b32 v71, v194, v70
	ds_bpermute_b32 v76, v194, v66
	ds_bpermute_b32 v77, v194, v67
	ds_bpermute_b32 v65, v194, v64
	s_waitcnt lgkmcnt(6)
	v_add_f32_e32 v68, v68, v69
	s_waitcnt lgkmcnt(4)
	v_pk_add_f32 v[72:73], v[72:73], v[74:75]
	s_waitcnt lgkmcnt(3)
	v_add_f32_e32 v70, v70, v71
	s_waitcnt lgkmcnt(1)
	v_pk_add_f32 v[76:77], v[66:67], v[76:77]
	s_waitcnt lgkmcnt(0)
	v_add_f32_e32 v110, v64, v65
	ds_bpermute_b32 v69, v195, v68
	ds_bpermute_b32 v74, v195, v72
	ds_bpermute_b32 v75, v195, v73
	ds_bpermute_b32 v71, v195, v70
	ds_bpermute_b32 v109, v195, v108
	ds_bpermute_b32 v78, v195, v76
	ds_bpermute_b32 v79, v195, v77
	ds_bpermute_b32 v111, v195, v110
	s_and_saveexec_b64 s[12:13], 15
	s_cbranch_execz .LBB0_272
	s_waitcnt lgkmcnt(0)
	v_add_f32_e32 v203, v110, v111
	v_add_f32_e32 v110, v68, v69
	v_add_f32_e32 v111, v70, v71
	v_add_f32_e32 v224, v108, v109
	v_mov_b64_e32 v[108:109], s[44:45]
	v_pk_add_f32 v[72:73], v[72:73], v[74:75]
	v_pk_add_f32 v[76:77], v[76:77], v[78:79]
	s_add_u32 s56, s16, s40
	s_addc_u32 s57, s17, s41
	v_mov_b32_e32 v64, v110
	v_mov_b32_e32 v65, v72
	s_mov_b64 vcc, 2
	v_cndmask_b32_e32 v64, v64, v111, vcc
	v_cndmask_b32_e32 v65, v65, v73, vcc
	s_mov_b64 vcc, 4
	v_cndmask_b32_e32 v64, v64, v224, vcc
	v_cndmask_b32_e32 v65, v65, v76, vcc
	s_mov_b64 vcc, 8
	v_cndmask_b32_e32 v64, v64, v203, vcc
	v_cndmask_b32_e32 v65, v65, v77, vcc
	v_add_f32_e32 v64, v64, v236
	v_add_f32_e32 v65, v65, v237
	global_store_dword v233, v65, s[56:57]
	s_nop 0
	v_mul_f32_e64 v110, |v64|, s62
	s_nop 0
	v_exp_f32_e32 v225, v110
	s_nop 0
	v_add_f32_e32 v114, 1.0, v225
	s_nop 0
	v_frexp_mant_f32_e32 v117, v114
	v_cvt_f64_f32_e32 v[110:111], v114
	s_nop 0
	v_frexp_exp_i32_f64_e32 v110, v[110:111]
	v_cmp_gt_f32_e32 vcc, s63, v117
	v_add_f32_e32 v116, -1.0, v114
	s_nop 0
	v_subbrev_co_u32_e32 v110, vcc, 0, v110, vcc
	v_sub_f32_e32 v120, v116, v114
	v_sub_f32_e32 v116, v225, v116
	v_add_f32_e32 v113, 1.0, v120
	s_nop 0
	v_add_f32_e32 v113, v116, v113
	v_sub_u32_e32 v116, 0, v110
	v_cvt_f32_i32_e32 v110, v110
	v_ldexp_f32 v112, v114, v116
	v_ldexp_f32 v114, v113, v116
	v_add_f32_e32 v116, 1.0, v112
	v_add_f32_e32 v118, -1.0, v112
	v_add_f32_e32 v120, -1.0, v116
	v_add_f32_e32 v122, 1.0, v118
	v_sub_f32_e32 v120, v112, v120
	v_sub_f32_e32 v112, v112, v122
	v_mul_f32_e32 v122, s50, v110
	v_add_f32_e32 v120, v114, v120
	v_add_f32_e32 v112, v114, v112
	v_fma_f32 v114, v110, s50, -v122
	v_add_f32_e32 v204, v116, v120
	v_fma_f32 v110, v110, s52, v114
	v_rcp_f32_e32 v114, v204
	v_add_f32_e32 v206, v118, v112
	v_sub_f32_e32 v116, v204, v116
	v_sub_f32_e32 v118, v206, v118
	v_mul_f32_e32 v214, v206, v114
	v_sub_f32_e32 v116, v120, v116
	v_mul_f32_e32 v216, v204, v214
	v_sub_f32_e32 v112, v112, v118
	v_fma_f32 v218, v214, v204, -v216
	v_add_f32_e32 v208, v122, v110
	v_fma_f32 v218, v214, v116, v218
	v_mov_b32_e32 v124, v122
	v_add_f32_e32 v220, v216, v218
	v_mov_b32_e32 v210, v110
	v_sub_f32_e32 v222, v206, v220
	v_sub_f32_e32 v216, v220, v216
	v_sub_f32_e32 v206, v206, v222
	v_sub_f32_e32 v216, v216, v218
	v_sub_f32_e32 v206, v206, v220
	s_nop 0
	v_add_f32_e32 v112, v112, v206
	s_nop 0
	v_add_f32_e32 v112, v216, v112
	s_nop 0
	v_add_f32_e32 v206, v222, v112
	v_mov_b32_e32 v126, v208
	v_mul_f32_e32 v216, v114, v206
	v_sub_f32_e32 v218, v222, v206
	v_mul_f32_e32 v220, v204, v216
	v_add_f32_e32 v112, v112, v218
	v_add_f32_e32 v218, v214, v216
	v_fma_f32 v204, v216, v204, -v220
	v_sub_f32_e32 v214, v218, v214
	v_fma_f32 v116, v216, v116, v204
	v_sub_f32_e32 v204, v216, v214
	v_add_f32_e32 v214, v220, v116
	s_nop 0
	v_sub_f32_e32 v216, v214, v220
	v_sub_f32_e32 v220, v206, v214
	v_sub_f32_e32 v116, v216, v116
	v_sub_f32_e32 v206, v206, v220
	v_cmp_neq_f32_e32 vcc, s64, v225
	v_sub_f32_e32 v206, v206, v214
	s_nop 0
	v_add_f32_e32 v112, v112, v206
	s_nop 0
	v_add_f32_e32 v112, v116, v112
	s_nop 0
	v_add_f32_e32 v112, v220, v112
	v_min_f32_e32 v64, 0, v64
	v_mul_f32_e32 v112, v114, v112
	s_nop 0
	v_add_f32_e32 v112, v204, v112
	s_nop 0
	v_add_f32_e32 v114, v218, v112
	s_nop 0
	v_sub_f32_e32 v116, v114, v218
	v_mul_f32_e32 v206, v114, v114
	v_sub_f32_e32 v112, v112, v116
	v_fma_f32 v116, v206, s46, v108
	v_ldexp_f32 v204, v114, 1
	v_mul_f32_e32 v114, v114, v206
	v_fma_f32 v116, v206, v116, s48
	s_nop 0
	v_mul_f32_e32 v114, v114, v116
	v_ldexp_f32 v112, v112, 1
	v_add_f32_e32 v116, v204, v114
	s_nop 0
	v_sub_f32_e32 v204, v116, v204
	v_mov_b32_e32 v120, v116
	v_sub_f32_e32 v114, v114, v204
	s_nop 0
	v_add_f32_e32 v204, v112, v114
	s_nop 0
	v_add_f32_e32 v206, v116, v204
	v_add_f32_e32 v112, v112, v114
	v_add_f32_e32 v114, v208, v206
	v_add_f32_e32 v124, v124, v210
	v_mov_b32_e32 v210, v206
	s_nop 0
	v_sub_f32_e32 v120, v210, v120
	v_mov_b32_e32 v118, v114
	v_mov_b32_e32 v210, v208
	v_mov_b32_e32 v212, v206
	v_sub_f32_e32 v118, v118, v126
	v_sub_f32_e32 v122, v210, v122
	v_sub_f32_e32 v126, v212, v118
	v_mov_b32_e32 v210, v122
	v_mov_b32_e32 v212, v114
	v_sub_f32_e32 v210, v110, v210
	v_sub_f32_e32 v118, v212, v118
	s_nop 0
	v_sub_f32_e32 v118, v124, v118
	v_sub_f32_e32 v110, v110, v122
	v_sub_f32_e32 v112, v112, v120
	v_add_f32_e32 v122, v126, v118
	v_add_f32_e32 v120, v112, v110
	v_add_f32_e32 v112, v110, v112
	v_sub_f32_e32 v116, v206, v116
	v_sub_f32_e32 v112, v112, v210
	v_mov_b32_e32 v118, v120
	v_sub_f32_e32 v116, v204, v116
	v_sub_f32_e32 v118, v118, v112
	v_sub_f32_e32 v112, v116, v112
	v_sub_f32_e32 v110, v110, v118
	s_nop 0
	v_add_f32_e32 v110, v112, v110
	v_add_f32_e32 v112, v122, v120
	s_nop 0
	v_add_f32_e32 v116, v114, v112
	s_nop 0
	v_sub_f32_e32 v114, v116, v114
	s_nop 0
	v_sub_f32_e32 v112, v112, v114
	s_nop 0
	v_add_f32_e32 v110, v110, v112
	s_nop 0
	v_add_f32_e32 v110, v116, v110
	s_nop 0
	v_cndmask_b32_e32 v110, v200, v110, vcc
	v_cmp_ngt_f32_e32 vcc, -1.0, v225
	s_nop 1
	v_cndmask_b32_e32 v110, v201, v110, vcc
	v_cmp_neq_f32_e32 vcc, -1.0, v225
	s_nop 1
	v_cndmask_b32_e32 v110, v202, v110, vcc
	v_cmp_lt_f32_e64 vcc, |v225|, s65
	s_nop 1
	v_cndmask_b32_e32 v110, v110, v225, vcc
	s_nop 0
	v_sub_f32_e32 v64, v64, v110
	s_nop 0
	global_store_dword v233, v64, s[56:57] offset:16
.LBB0_272:
	s_or_b64 exec, exec, s[12:13]
	s_and_b64 vcc, exec, s[10:11]
	v_mov_b32_e32 v64, v239
	s_cbranch_vccnz .LBB0_274
	s_add_u32 s12, s16, s36
	s_addc_u32 s13, s17, s37
.LBB0_274:
	v_lshlrev_b32_e32 v66, 16, v162
	v_and_b32_e32 v67, 0xffff0000, v162
	v_pk_mul_f32 v[66:67], v[64:65], v[66:67] op_sel_hi:[0,1]
	v_and_b32_e32 v113, 0xffff0000, v105
	v_lshlrev_b32_e32 v68, 16, v163
	s_waitcnt lgkmcnt(7)
	v_and_b32_e32 v69, 0xffff0000, v163
	v_cndmask_b32_e64 v70, v16, v66, s[6:7]
	v_lshlrev_b32_e32 v112, 16, v105
	v_mul_f32_e32 v66, v113, v113
	v_and_b32_e32 v117, 0xffff0000, v103
	v_and_b32_e32 v116, 0xffff0000, v102
	v_pk_mul_f32 v[68:69], v[64:65], v[68:69] op_sel_hi:[0,1]
	s_waitcnt lgkmcnt(4)
	v_cndmask_b32_e64 v71, v17, v67, s[6:7]
	s_waitcnt lgkmcnt(1)
	v_and_b32_e32 v79, 0xffff0000, v104
	v_pk_fma_f32 v[108:109], v[112:113], v[112:113], v[66:67] op_sel_hi:[1,1,0]
	v_lshlrev_b32_e32 v115, 16, v103
	v_lshlrev_b32_e32 v114, 16, v102
	v_pk_mul_f32 v[66:67], v[116:117], v[116:117]
	v_cndmask_b32_e64 v73, v19, v69, s[6:7]
	v_cndmask_b32_e64 v72, v18, v68, s[6:7]
	v_lshlrev_b32_e32 v78, 16, v104
	v_pk_fma_f32 v[118:119], v[114:115], v[114:115], v[66:67]
	ds_read_b128 v[66:69], v234
	v_mul_f32_e32 v102, v79, v79
	s_waitcnt lgkmcnt(0)
	v_pk_fma_f32 v[110:111], v[78:79], v[78:79], v[102:103] op_sel_hi:[1,1,0]
	v_lshlrev_b32_e32 v120, 16, v100
	v_and_b32_e32 v121, 0xffff0000, v100
	v_lshlrev_b32_e32 v122, 16, v101
	v_and_b32_e32 v123, 0xffff0000, v101
	v_lshlrev_b32_e32 v125, 16, v98
	v_and_b32_e32 v127, 0xffff0000, v98
	v_lshlrev_b32_e32 v204, 16, v99
	v_and_b32_e32 v205, 0xffff0000, v99
	ds_read_b128 v[98:101], v234 offset:1024
	ds_read_b128 v[102:105], v234 offset:2048
	v_mov_b32_e32 v124, v110
	v_mov_b32_e32 v206, v108
	v_pk_add_f32 v[208:209], v[110:111], v[108:109]
	ds_read_b128 v[108:111], v234 offset:3072
	v_mov_b32_e32 v207, v125
	v_mul_f32_e32 v65, v127, v127
	v_pk_mul_f32 v[206:207], v[124:125], v[206:207]
	v_pk_add_f32 v[118:119], v[118:119], v[118:119] op_sel:[0,1] op_sel_hi:[1,0]
	v_mul_f32_e32 v124, v121, v121
	v_mov_b32_e32 v209, v207
	v_mov_b32_e32 v119, v65
	v_pk_fma_f32 v[206:207], v[120:121], v[120:121], v[124:125] op_sel_hi:[1,1,0]
	v_mul_f32_e32 v124, v123, v123
	v_mul_f32_e32 v77, v204, v204
	v_mul_f32_e32 v126, v205, v205
	v_pk_add_f32 v[118:119], v[208:209], v[118:119]
	v_pk_fma_f32 v[208:209], v[122:123], v[122:123], v[124:125] op_sel_hi:[1,1,0]
	v_mov_b32_e32 v207, v77
	v_mov_b32_e32 v209, v126
	v_pk_add_f32 v[206:207], v[206:207], v[208:209]
	v_lshlrev_b32_e32 v74, 16, v160
	v_pk_add_f32 v[118:119], v[118:119], v[206:207]
	v_and_b32_e32 v75, 0xffff0000, v160
	v_add_f32_e32 v65, v118, v119
	ds_bpermute_b32 v118, v190, v65
	v_lshlrev_b32_e32 v76, 16, v161
	v_and_b32_e32 v77, 0xffff0000, v161
	v_pk_mul_f32 v[76:77], v[64:65], v[76:77] op_sel_hi:[0,1]
	v_pk_mul_f32 v[74:75], v[64:65], v[74:75] op_sel_hi:[0,1]
	s_waitcnt lgkmcnt(0)
	v_add_f32_e32 v65, v65, v118
	v_cndmask_b32_e64 v119, v21, v75, s[6:7]
	ds_bpermute_b32 v75, v191, v65
	v_cndmask_b32_e64 v207, v23, v77, s[6:7]
	v_cndmask_b32_e64 v206, v22, v76, s[6:7]
	v_lshlrev_b32_e32 v76, 16, v159
	v_and_b32_e32 v77, 0xffff0000, v159
	s_waitcnt lgkmcnt(0)
	v_add_f32_e32 v65, v65, v75
	ds_bpermute_b32 v124, v192, v65
	v_pk_mul_f32 v[76:77], v[64:65], v[76:77] op_sel_hi:[0,1]
	v_cndmask_b32_e64 v118, v20, v74, s[6:7]
	v_lshlrev_b32_e32 v74, 16, v158
	v_and_b32_e32 v75, 0xffff0000, v158
	s_waitcnt lgkmcnt(0)
	v_add_f32_e32 v65, v65, v124
	ds_bpermute_b32 v124, v193, v65
	v_pk_mul_f32 v[74:75], v[64:65], v[74:75] op_sel_hi:[0,1]
	v_cndmask_b32_e64 v211, v27, v77, s[6:7]
	v_cndmask_b32_e64 v209, v25, v75, s[6:7]
	v_cndmask_b32_e64 v208, v24, v74, s[6:7]
	s_waitcnt lgkmcnt(0)
	v_add_f32_e32 v65, v65, v124
	ds_bpermute_b32 v77, v194, v65
	v_cndmask_b32_e64 v210, v26, v76, s[6:7]
	v_lshlrev_b32_e32 v74, 16, v156
	v_and_b32_e32 v75, 0xffff0000, v156
	v_lshlrev_b32_e32 v76, 16, v157
	s_waitcnt lgkmcnt(0)
	v_add_f32_e32 v124, v65, v77
	ds_bpermute_b32 v126, v195, v124
	v_and_b32_e32 v77, 0xffff0000, v157
	v_pk_mul_f32 v[76:77], v[64:65], v[76:77] op_sel_hi:[0,1]
	v_pk_mul_f32 v[64:65], v[64:65], v[74:75] op_sel_hi:[0,1]
	v_cndmask_b32_e64 v213, v29, v65, s[6:7]
	s_waitcnt lgkmcnt(0)
	v_add_f32_e32 v65, v124, v126
	v_fmamk_f32 v65, v65, 0x3a800000, v197
	v_mul_f32_e32 v74, 0x4b800000, v65
	v_cmp_gt_f32_e32 vcc, s59, v65
	v_cndmask_b32_e64 v212, v28, v64, s[6:7]
	v_cndmask_b32_e64 v215, v31, v77, s[6:7]
	v_cndmask_b32_e32 v65, v65, v74, vcc
	v_rsq_f32_e32 v65, v65
	v_cndmask_b32_e64 v214, v30, v76, s[6:7]
	v_mov_b32_e32 v126, v125
	v_mul_f32_e32 v64, 0x45800000, v65
	v_cndmask_b32_e32 v64, v65, v64, vcc
	v_mul_f32_e32 v124, 0.5, v64
	v_pk_mul_f32 v[64:65], v[124:125], v[78:79] op_sel_hi:[0,1]
	v_pk_mul_f32 v[74:75], v[124:125], v[112:113] op_sel_hi:[0,1]
	s_waitcnt lgkmcnt(9)
	v_pk_fma_f32 v[76:77], v[66:67], v[64:65], v[70:71]
	v_mov_b32_e32 v64, v114
	v_mov_b32_e32 v65, v116
	v_mov_b32_e32 v116, v115
	v_pk_fma_f32 v[74:75], v[68:69], v[74:75], v[72:73]
	v_pk_mul_f32 v[64:65], v[124:125], v[64:65] op_sel_hi:[0,1]
	v_pk_mul_f32 v[66:67], v[124:125], v[116:117] op_sel_hi:[0,1]
	v_pk_mul_f32 v[78:79], v[204:205], v[124:125] op_sel_hi:[1,0]
	s_waitcnt lgkmcnt(8)
	v_pk_fma_f32 v[70:71], v[100:101], v[66:67], v[206:207]
	v_pk_fma_f32 v[72:73], v[98:99], v[64:65], v[118:119]
	v_pk_mul_f32 v[66:67], v[124:125], v[120:121] op_sel_hi:[0,1]
	s_waitcnt lgkmcnt(6)
	v_pk_fma_f32 v[98:99], v[110:111], v[78:79], v[214:215]
	v_pk_mul_f32 v[78:79], v[74:75], v[74:75]
	v_pk_mul_f32 v[100:101], v[76:77], v[76:77]
	v_pk_fma_f32 v[66:67], v[102:103], v[66:67], v[208:209]
	v_pk_mov_b32 v[102:103], v[100:101], v[78:79] op_sel:[1,0]
	v_mov_b32_e32 v101, v79
	v_pk_add_f32 v[78:79], v[102:103], v[100:101]
	v_pk_mul_f32 v[64:65], v[124:125], v[122:123] op_sel_hi:[0,1]
	v_pk_add_f32 v[78:79], v[78:79], v[78:79] op_sel_hi:[0,1]
	v_pk_mul_f32 v[100:101], v[70:71], v[70:71]
	v_pk_mul_f32 v[102:103], v[72:73], v[72:73]
	v_pk_fma_f32 v[64:65], v[104:105], v[64:65], v[210:211]
	v_pk_mov_b32 v[104:105], v[102:103], v[100:101] op_sel:[1,0]
	v_mov_b32_e32 v103, v101
	v_mul_f32_e32 v78, v66, v66
	v_pk_mul_f32 v[68:69], v[126:127], v[124:125] op_sel_hi:[1,0]
	v_pk_add_f32 v[100:101], v[104:105], v[102:103]
	v_pk_fma_f32 v[102:103], v[66:67], v[66:67], v[78:79] op_sel_hi:[1,1,0]
	v_mul_f32_e32 v78, v64, v64
	v_pk_fma_f32 v[68:69], v[108:109], v[68:69], v[212:213]
	v_pk_add_f32 v[100:101], v[100:101], v[100:101] op_sel_hi:[0,1]
	v_pk_fma_f32 v[104:105], v[64:65], v[64:65], v[78:79] op_sel_hi:[1,1,0]
	v_mul_f32_e32 v102, v68, v68
	v_mul_f32_e32 v104, v69, v69
	v_mul_f32_e32 v78, v98, v98
	v_mul_f32_e32 v100, v99, v99
	v_pk_add_f32 v[102:103], v[102:103], v[104:105]
	v_pk_add_f32 v[78:79], v[78:79], v[100:101]
	s_nop 0
	v_pk_add_f32 v[78:79], v[102:103], v[78:79]
	s_nop 0
	v_add_f32_e32 v78, v78, v79
	ds_bpermute_b32 v79, v190, v78
	s_waitcnt lgkmcnt(0)
	v_add_f32_e32 v78, v78, v79
	ds_bpermute_b32 v79, v191, v78
	s_waitcnt lgkmcnt(0)
	v_add_f32_e32 v78, v78, v79
	ds_bpermute_b32 v79, v192, v78
	s_waitcnt lgkmcnt(0)
	v_add_f32_e32 v78, v78, v79
	ds_bpermute_b32 v79, v193, v78
	s_waitcnt lgkmcnt(0)
	v_add_f32_e32 v78, v78, v79
	ds_bpermute_b32 v79, v194, v78
	s_waitcnt lgkmcnt(0)
	v_add_f32_e32 v78, v78, v79
	ds_bpermute_b32 v79, v195, v78
	s_waitcnt lgkmcnt(0)
	v_add_f32_e32 v78, v78, v79
	v_fmamk_f32 v78, v78, 0x3a800000, v197
	v_mul_f32_e32 v79, 0x4b800000, v78
	v_cmp_gt_f32_e32 vcc, s59, v78
	s_nop 1
	v_cndmask_b32_e32 v79, v78, v79, vcc
	v_rsq_f32_e32 v79, v79
	s_nop 0
	v_mul_f32_e32 v100, 0x45800000, v79
	v_cndmask_b32_e32 v100, v79, v100, vcc
	v_pk_mul_f32 v[102:103], v[74:75], v[100:101] op_sel_hi:[1,0]
	v_pk_mul_f32 v[104:105], v[76:77], v[100:101] op_sel_hi:[1,0]
	s_nop 0
	v_cvt_pk_bf16_f32 v104, v104, v105
	v_cvt_pk_bf16_f32 v105, v102, v103
	global_store_dwordx2 v[106:107], v[104:105], off offset:2048
	v_pk_mul_f32 v[102:103], v[70:71], v[100:101] op_sel_hi:[1,0]
	v_pk_mul_f32 v[104:105], v[72:73], v[100:101] op_sel_hi:[1,0]
	s_nop 0
	v_cvt_pk_bf16_f32 v104, v104, v105
	v_cvt_pk_bf16_f32 v105, v102, v103
	global_store_dwordx2 v[106:107], v[104:105], off offset:2560
	v_pk_mul_f32 v[102:103], v[64:65], v[100:101] op_sel_hi:[1,0]
	v_pk_mul_f32 v[104:105], v[66:67], v[100:101] op_sel_hi:[1,0]
	s_nop 0
	v_cvt_pk_bf16_f32 v104, v104, v105
	v_cvt_pk_bf16_f32 v105, v102, v103
	global_store_dwordx2 v[106:107], v[104:105], off offset:3072
	v_pk_mul_f32 v[102:103], v[98:99], v[100:101] op_sel_hi:[1,0]
	v_pk_mul_f32 v[104:105], v[68:69], v[100:101] op_sel_hi:[1,0]
	s_nop 0
	v_cvt_pk_bf16_f32 v104, v104, v105
	v_cvt_pk_bf16_f32 v105, v102, v103
	global_store_dwordx2 v[106:107], v[104:105], off offset:3584
	s_and_saveexec_b64 s[56:57], s[4:5]
	s_cbranch_execz .LBB0_276
	v_mul_f32_e32 v79, 0x4f800000, v78
	v_cmp_gt_f32_e32 vcc, s61, v78
	s_nop 1
	v_cndmask_b32_e32 v78, v78, v79, vcc
	v_sqrt_f32_e32 v79, v78
	s_nop 0
	v_add_u32_e32 v101, -1, v79
	v_fma_f32 v103, -v101, v79, v78
	v_add_u32_e32 v102, 1, v79
	v_cmp_ge_f32_e64 s[12:13], 0, v103
	s_nop 1
	v_cndmask_b32_e64 v101, v79, v101, s[12:13]
	v_fma_f32 v79, -v102, v79, v78
	v_cmp_lt_f32_e64 s[12:13], 0, v79
	s_nop 1
	v_cndmask_b32_e64 v79, v101, v102, s[12:13]
	v_mul_f32_e32 v101, 0x37800000, v79
	v_cndmask_b32_e32 v79, v79, v101, vcc
	v_cmp_class_f32_e32 vcc, v78, v198
	s_add_u32 s12, s16, s36
	s_addc_u32 s13, s17, s37
	v_cndmask_b32_e32 v78, v79, v78, vcc
	global_store_dword v196, v78, s[12:13] offset:4
.LBB0_276:
	s_or_b64 exec, exec, s[56:57]
	ds_read_b128 v[102:105], v235
	ds_read_b128 v[106:109], v230 offset:3072
	ds_read_b128 v[110:113], v230 offset:2048
	ds_read_b128 v[114:117], v230 offset:1024
	ds_read_b128 v[118:121], v230
	v_mul_f32_e32 v76, v76, v100
	v_mul_f32_e32 v74, v74, v100
	v_mul_f32_e32 v72, v72, v100
	v_mul_f32_e32 v70, v70, v100
	v_mul_f32_e32 v66, v66, v100
	v_mul_f32_e32 v64, v64, v100
	v_mul_f32_e32 v68, v68, v100
	v_mul_f32_e32 v98, v98, v100
	s_waitcnt lgkmcnt(4)
	v_mul_f32_e32 v76, v76, v102
	v_mul_f32_e32 v74, v74, v104
	s_waitcnt lgkmcnt(1)
	v_pk_fma_f32 v[116:117], v[116:117], v[76:77], 0 op_sel_hi:[1,0,0]
	s_waitcnt lgkmcnt(0)
	v_pk_fma_f32 v[78:79], v[120:121], v[76:77], 0 op_sel_hi:[1,0,0]
	v_pk_fma_f32 v[118:119], v[118:119], v[76:77], 0 op_sel_hi:[1,0,0]
	v_pk_fma_f32 v[114:115], v[114:115], v[76:77], 0 op_sel_hi:[1,0,0]
	v_mul_f32_e32 v76, v77, v100
	v_mul_f32_e32 v76, v76, v103
	v_pk_fma_f32 v[102:103], v[112:113], v[76:77], v[78:79] op_sel_hi:[1,0,1]
	v_pk_fma_f32 v[118:119], v[110:111], v[76:77], v[118:119] op_sel_hi:[1,0,1]
	v_pk_fma_f32 v[120:121], v[76:77], v[108:109], v[116:117] op_sel_hi:[0,1,1]
	v_pk_fma_f32 v[122:123], v[76:77], v[106:107], v[114:115] op_sel_hi:[0,1,1]
	ds_read_b128 v[76:79], v230 offset:19456
	ds_read_b128 v[106:109], v230 offset:18432
	ds_read_b128 v[110:113], v230 offset:17408
	ds_read_b128 v[114:117], v230 offset:16384
	s_waitcnt lgkmcnt(1)
	v_pk_fma_f32 v[110:111], v[74:75], v[110:111], v[122:123] op_sel_hi:[0,1,1]
	s_waitcnt lgkmcnt(0)
	v_pk_fma_f32 v[114:115], v[74:75], v[114:115], v[118:119] op_sel_hi:[0,1,1]
	v_pk_fma_f32 v[102:103], v[74:75], v[116:117], v[102:103] op_sel_hi:[0,1,1]
	v_pk_fma_f32 v[112:113], v[74:75], v[112:113], v[120:121] op_sel_hi:[0,1,1]
	v_mul_f32_e32 v74, v75, v100
	v_mul_f32_e32 v74, v74, v105
	v_pk_fma_f32 v[118:119], v[74:75], v[108:109], v[102:103] op_sel_hi:[0,1,1]
	v_pk_fma_f32 v[120:121], v[74:75], v[106:107], v[114:115] op_sel_hi:[0,1,1]
	v_pk_fma_f32 v[78:79], v[74:75], v[78:79], v[112:113] op_sel_hi:[0,1,1]
	v_pk_fma_f32 v[122:123], v[74:75], v[76:77], v[110:111] op_sel_hi:[0,1,1]
	ds_read_b128 v[74:77], v235 offset:1024
	ds_read_b128 v[102:105], v230 offset:35840
	ds_read_b128 v[106:109], v230 offset:34816
	ds_read_b128 v[110:113], v230 offset:33792
	ds_read_b128 v[114:117], v230 offset:32768
	s_waitcnt lgkmcnt(4)
	v_mul_f32_e32 v72, v72, v74
	v_mul_f32_e32 v70, v70, v76
	s_waitcnt lgkmcnt(1)
	v_pk_fma_f32 v[110:111], v[110:111], v[72:73], v[122:123] op_sel_hi:[1,0,1]
	s_waitcnt lgkmcnt(0)
	v_pk_fma_f32 v[114:115], v[114:115], v[72:73], v[120:121] op_sel_hi:[1,0,1]
	v_pk_fma_f32 v[116:117], v[116:117], v[72:73], v[118:119] op_sel_hi:[1,0,1]
	v_pk_fma_f32 v[78:79], v[112:113], v[72:73], v[78:79] op_sel_hi:[1,0,1]
	v_mul_f32_e32 v72, v73, v100
	v_mul_f32_e32 v72, v72, v75
	v_pk_fma_f32 v[116:117], v[108:109], v[72:73], v[116:117] op_sel_hi:[1,0,1]
	v_pk_fma_f32 v[114:115], v[106:107], v[72:73], v[114:115] op_sel_hi:[1,0,1]
	v_pk_fma_f32 v[78:79], v[72:73], v[104:105], v[78:79] op_sel_hi:[0,1,1]
	v_pk_fma_f32 v[118:119], v[72:73], v[102:103], v[110:111] op_sel_hi:[0,1,1]
	ds_read_b128 v[72:75], v230 offset:52224
	ds_read_b128 v[102:105], v230 offset:51200
	ds_read_b128 v[106:109], v230 offset:50176
	ds_read_b128 v[110:113], v230 offset:49152
	s_waitcnt lgkmcnt(1)
	v_pk_fma_f32 v[106:107], v[70:71], v[106:107], v[118:119] op_sel_hi:[0,1,1]
	s_waitcnt lgkmcnt(0)
	v_pk_fma_f32 v[110:111], v[70:71], v[110:111], v[114:115] op_sel_hi:[0,1,1]
	v_pk_fma_f32 v[112:113], v[70:71], v[112:113], v[116:117] op_sel_hi:[0,1,1]
	v_pk_fma_f32 v[78:79], v[70:71], v[108:109], v[78:79] op_sel_hi:[0,1,1]
	v_mul_f32_e32 v70, v71, v100
	v_mul_f32_e32 v70, v70, v77
	v_pk_fma_f32 v[114:115], v[70:71], v[104:105], v[112:113] op_sel_hi:[0,1,1]
	v_pk_fma_f32 v[116:117], v[70:71], v[102:103], v[110:111] op_sel_hi:[0,1,1]
	v_pk_fma_f32 v[78:79], v[70:71], v[74:75], v[78:79] op_sel_hi:[0,1,1]
	v_pk_fma_f32 v[118:119], v[70:71], v[72:73], v[106:107] op_sel_hi:[0,1,1]
	ds_read_b128 v[70:73], v235 offset:2048
	ds_read_b128 v[74:77], v231 offset:3072
	ds_read_b128 v[102:105], v231 offset:2048
	ds_read_b128 v[106:109], v231 offset:1024
	ds_read_b128 v[110:113], v231
	s_waitcnt lgkmcnt(4)
	v_mul_f32_e32 v66, v66, v70
	v_mul_f32_e32 v64, v64, v72
	s_waitcnt lgkmcnt(1)
	v_pk_fma_f32 v[106:107], v[106:107], v[66:67], v[118:119] op_sel_hi:[1,0,1]
	s_waitcnt lgkmcnt(0)
	v_pk_fma_f32 v[110:111], v[110:111], v[66:67], v[116:117] op_sel_hi:[1,0,1]
	v_pk_fma_f32 v[112:113], v[112:113], v[66:67], v[114:115] op_sel_hi:[1,0,1]
	v_pk_fma_f32 v[78:79], v[108:109], v[66:67], v[78:79] op_sel_hi:[1,0,1]
	v_mul_f32_e32 v66, v67, v100
	v_mul_f32_e32 v66, v66, v71
	v_pk_fma_f32 v[70:71], v[104:105], v[66:67], v[112:113] op_sel_hi:[1,0,1]
	v_pk_fma_f32 v[114:115], v[102:103], v[66:67], v[110:111] op_sel_hi:[1,0,1]
	v_pk_fma_f32 v[78:79], v[66:67], v[76:77], v[78:79] op_sel_hi:[0,1,1]
	v_pk_fma_f32 v[66:67], v[66:67], v[74:75], v[106:107] op_sel_hi:[0,1,1]
	ds_read_b128 v[74:77], v231 offset:19456
	ds_read_b128 v[102:105], v231 offset:18432
	ds_read_b128 v[106:109], v231 offset:17408
	ds_read_b128 v[110:113], v231 offset:16384
	s_waitcnt lgkmcnt(1)
	v_pk_fma_f32 v[66:67], v[64:65], v[106:107], v[66:67] op_sel_hi:[0,1,1]
	s_waitcnt lgkmcnt(0)
	v_pk_fma_f32 v[110:111], v[64:65], v[110:111], v[114:115] op_sel_hi:[0,1,1]
	v_pk_fma_f32 v[70:71], v[64:65], v[112:113], v[70:71] op_sel_hi:[0,1,1]
	v_pk_fma_f32 v[78:79], v[64:65], v[108:109], v[78:79] op_sel_hi:[0,1,1]
	v_mul_f32_e32 v64, v65, v100
	v_mul_f32_e32 v64, v64, v73
	v_pk_fma_f32 v[112:113], v[64:65], v[104:105], v[70:71] op_sel_hi:[0,1,1]
	v_pk_fma_f32 v[110:111], v[64:65], v[102:103], v[110:111] op_sel_hi:[0,1,1]
	v_pk_fma_f32 v[78:79], v[64:65], v[76:77], v[78:79] op_sel_hi:[0,1,1]
	v_pk_fma_f32 v[114:115], v[64:65], v[74:75], v[66:67] op_sel_hi:[0,1,1]
	ds_read_b128 v[64:67], v235 offset:3072
	ds_read_b128 v[70:73], v231 offset:35840
	ds_read_b128 v[74:77], v231 offset:34816
	ds_read_b128 v[102:105], v231 offset:33792
	ds_read_b128 v[106:109], v231 offset:32768
	s_waitcnt lgkmcnt(4)
	v_mul_f32_e32 v64, v68, v64
	v_mul_f32_e32 v66, v98, v66
	s_waitcnt lgkmcnt(1)
	v_pk_fma_f32 v[102:103], v[102:103], v[64:65], v[114:115] op_sel_hi:[1,0,1]
	s_waitcnt lgkmcnt(0)
	v_pk_fma_f32 v[106:107], v[106:107], v[64:65], v[110:111] op_sel_hi:[1,0,1]
	v_pk_fma_f32 v[108:109], v[108:109], v[64:65], v[112:113] op_sel_hi:[1,0,1]
	v_pk_fma_f32 v[78:79], v[104:105], v[64:65], v[78:79] op_sel_hi:[1,0,1]
	v_mul_f32_e32 v64, v69, v100
	v_mul_f32_e32 v68, v64, v65
	v_pk_fma_f32 v[104:105], v[76:77], v[68:69], v[108:109] op_sel_hi:[1,0,1]
	v_pk_fma_f32 v[106:107], v[74:75], v[68:69], v[106:107] op_sel_hi:[1,0,1]
	v_pk_fma_f32 v[64:65], v[68:69], v[72:73], v[78:79] op_sel_hi:[0,1,1]
	v_pk_fma_f32 v[102:103], v[68:69], v[70:71], v[102:103] op_sel_hi:[0,1,1]
	ds_read_b128 v[68:71], v231 offset:52224
	ds_read_b128 v[72:75], v231 offset:51200
	ds_read_b128 v[76:79], v231 offset:50176
	ds_read_b128 v[108:111], v231 offset:49152
	s_waitcnt lgkmcnt(1)
	v_pk_fma_f32 v[76:77], v[66:67], v[76:77], v[102:103] op_sel_hi:[0,1,1]
	s_waitcnt lgkmcnt(0)
	v_pk_fma_f32 v[106:107], v[66:67], v[108:109], v[106:107] op_sel_hi:[0,1,1]
	v_pk_fma_f32 v[104:105], v[66:67], v[110:111], v[104:105] op_sel_hi:[0,1,1]
	v_pk_fma_f32 v[64:65], v[66:67], v[78:79], v[64:65] op_sel_hi:[0,1,1]
	v_mul_f32_e32 v66, v99, v100
	v_mul_f32_e32 v78, v66, v67
	v_pk_fma_f32 v[64:65], v[78:79], v[70:71], v[64:65] op_sel_hi:[0,1,1]
	v_pk_fma_f32 v[70:71], v[78:79], v[68:69], v[76:77] op_sel_hi:[0,1,1]
	ds_bpermute_b32 v77, v190, v64
	ds_bpermute_b32 v68, v190, v70
	v_pk_fma_f32 v[66:67], v[78:79], v[74:75], v[104:105] op_sel_hi:[0,1,1]
	v_pk_fma_f32 v[72:73], v[78:79], v[72:73], v[106:107] op_sel_hi:[0,1,1]
	ds_bpermute_b32 v74, v190, v72
	s_waitcnt lgkmcnt(2)
	v_add_f32_e32 v64, v64, v77
	ds_bpermute_b32 v77, v191, v64
	s_waitcnt lgkmcnt(2)
	v_add_f32_e32 v68, v70, v68
	ds_bpermute_b32 v75, v190, v73
	ds_bpermute_b32 v70, v190, v71
	ds_bpermute_b32 v76, v190, v66
	s_waitcnt lgkmcnt(3)
	v_add_f32_e32 v64, v64, v77
	ds_bpermute_b32 v77, v192, v64
	s_waitcnt lgkmcnt(3)
	v_pk_add_f32 v[72:73], v[72:73], v[74:75]
	s_waitcnt lgkmcnt(2)
	v_add_f32_e32 v70, v71, v70
	ds_bpermute_b32 v69, v191, v68
	ds_bpermute_b32 v74, v191, v72
	s_waitcnt lgkmcnt(2)
	v_add_f32_e32 v64, v64, v77
	ds_bpermute_b32 v77, v193, v64
	ds_bpermute_b32 v75, v191, v73
	ds_bpermute_b32 v71, v191, v70
	s_waitcnt lgkmcnt(4)
	v_add_f32_e32 v68, v68, v69
	ds_bpermute_b32 v69, v192, v68
	s_waitcnt lgkmcnt(3)
	v_add_f32_e32 v64, v64, v77
	ds_bpermute_b32 v77, v194, v64
	s_waitcnt lgkmcnt(3)
	v_pk_add_f32 v[72:73], v[72:73], v[74:75]
	s_waitcnt lgkmcnt(2)
	v_add_f32_e32 v70, v70, v71
	ds_bpermute_b32 v74, v192, v72
	ds_bpermute_b32 v75, v192, v73
	s_waitcnt lgkmcnt(2)
	v_add_f32_e32 v98, v64, v77
	ds_bpermute_b32 v77, v190, v67
	ds_bpermute_b32 v64, v190, v65
	ds_bpermute_b32 v71, v192, v70
	v_add_f32_e32 v68, v68, v69
	s_waitcnt lgkmcnt(3)
	v_pk_add_f32 v[72:73], v[72:73], v[74:75]
	s_waitcnt lgkmcnt(2)
	v_pk_add_f32 v[66:67], v[66:67], v[76:77]
	s_waitcnt lgkmcnt(1)
	v_add_f32_e32 v64, v65, v64
	ds_bpermute_b32 v76, v191, v66
	ds_bpermute_b32 v77, v191, v67
	ds_bpermute_b32 v65, v191, v64
	s_waitcnt lgkmcnt(3)
	v_add_f32_e32 v70, v70, v71
	ds_bpermute_b32 v69, v193, v68
	ds_bpermute_b32 v74, v193, v72
	s_waitcnt lgkmcnt(3)
	v_pk_add_f32 v[66:67], v[66:67], v[76:77]
	s_waitcnt lgkmcnt(2)
	v_add_f32_e32 v64, v64, v65
	ds_bpermute_b32 v76, v192, v66
	ds_bpermute_b32 v77, v192, v67
	ds_bpermute_b32 v65, v192, v64
	ds_bpermute_b32 v75, v193, v73
	ds_bpermute_b32 v71, v193, v70
	s_waitcnt lgkmcnt(6)
	v_add_f32_e32 v68, v68, v69
	s_waitcnt lgkmcnt(3)
	v_pk_add_f32 v[66:67], v[66:67], v[76:77]
	s_waitcnt lgkmcnt(2)
	v_add_f32_e32 v64, v64, v65
	ds_bpermute_b32 v76, v193, v66
	ds_bpermute_b32 v77, v193, v67
	ds_bpermute_b32 v65, v193, v64
	s_waitcnt lgkmcnt(4)
	v_pk_add_f32 v[72:73], v[72:73], v[74:75]
	s_waitcnt lgkmcnt(3)
	v_add_f32_e32 v70, v70, v71
	ds_bpermute_b32 v69, v194, v68
	s_waitcnt lgkmcnt(2)
	v_pk_add_f32 v[66:67], v[66:67], v[76:77]
	s_waitcnt lgkmcnt(1)
	v_add_f32_e32 v64, v64, v65
	ds_bpermute_b32 v74, v194, v72
	ds_bpermute_b32 v75, v194, v73
	ds_bpermute_b32 v71, v194, v70
	ds_bpermute_b32 v76, v194, v66
	ds_bpermute_b32 v77, v194, v67
	ds_bpermute_b32 v65, v194, v64
	s_waitcnt lgkmcnt(6)
	v_add_f32_e32 v68, v68, v69
	s_waitcnt lgkmcnt(4)
	v_pk_add_f32 v[72:73], v[72:73], v[74:75]
	s_waitcnt lgkmcnt(3)
	v_add_f32_e32 v70, v70, v71
	s_waitcnt lgkmcnt(1)
	v_pk_add_f32 v[76:77], v[66:67], v[76:77]
	s_waitcnt lgkmcnt(0)
	v_add_f32_e32 v100, v64, v65
	ds_bpermute_b32 v69, v195, v68
	ds_bpermute_b32 v74, v195, v72
	ds_bpermute_b32 v75, v195, v73
	ds_bpermute_b32 v71, v195, v70
	ds_bpermute_b32 v99, v195, v98
	ds_bpermute_b32 v78, v195, v76
	ds_bpermute_b32 v79, v195, v77
	ds_bpermute_b32 v101, v195, v100
	s_and_saveexec_b64 s[12:13], 15
	s_cbranch_execz .LBB0_278
	s_waitcnt lgkmcnt(0)
	v_add_f32_e32 v203, v100, v101
	v_add_f32_e32 v100, v68, v69
	v_add_f32_e32 v101, v70, v71
	v_add_f32_e32 v214, v98, v99
	v_mov_b64_e32 v[98:99], s[44:45]
	v_pk_add_f32 v[72:73], v[72:73], v[74:75]
	v_pk_add_f32 v[76:77], v[76:77], v[78:79]
	s_add_u32 s56, s16, s40
	s_addc_u32 s57, s17, s41
	v_mov_b32_e32 v64, v100
	v_mov_b32_e32 v65, v72
	s_mov_b64 vcc, 2
	v_cndmask_b32_e32 v64, v64, v101, vcc
	v_cndmask_b32_e32 v65, v65, v73, vcc
	s_mov_b64 vcc, 4
	v_cndmask_b32_e32 v64, v64, v214, vcc
	v_cndmask_b32_e32 v65, v65, v76, vcc
	s_mov_b64 vcc, 8
	v_cndmask_b32_e32 v64, v64, v203, vcc
	v_cndmask_b32_e32 v65, v65, v77, vcc
	v_add_f32_e32 v64, v64, v236
	v_add_f32_e32 v65, v65, v237
	global_store_dword v233, v65, s[56:57] offset:32
	s_nop 0
	v_mul_f32_e64 v100, |v64|, s62
	s_nop 0
	v_exp_f32_e32 v215, v100
	s_nop 0
	v_add_f32_e32 v104, 1.0, v215
	s_nop 0
	v_frexp_mant_f32_e32 v107, v104
	v_cvt_f64_f32_e32 v[100:101], v104
	s_nop 0
	v_frexp_exp_i32_f64_e32 v100, v[100:101]
	v_cmp_gt_f32_e32 vcc, s63, v107
	v_add_f32_e32 v106, -1.0, v104
	s_nop 0
	v_subbrev_co_u32_e32 v100, vcc, 0, v100, vcc
	v_sub_f32_e32 v110, v106, v104
	v_sub_f32_e32 v106, v215, v106
	v_add_f32_e32 v103, 1.0, v110
	s_nop 0
	v_add_f32_e32 v103, v106, v103
	v_sub_u32_e32 v106, 0, v100
	v_cvt_f32_i32_e32 v100, v100
	v_ldexp_f32 v102, v104, v106
	v_ldexp_f32 v104, v103, v106
	v_add_f32_e32 v106, 1.0, v102
	v_add_f32_e32 v108, -1.0, v102
	v_add_f32_e32 v110, -1.0, v106
	v_add_f32_e32 v112, 1.0, v108
	v_sub_f32_e32 v110, v102, v110
	v_sub_f32_e32 v102, v102, v112
	v_mul_f32_e32 v112, s50, v100
	v_add_f32_e32 v110, v104, v110
	v_add_f32_e32 v102, v104, v102
	v_fma_f32 v104, v100, s50, -v112
	v_add_f32_e32 v118, v106, v110
	v_fma_f32 v100, v100, s52, v104
	v_rcp_f32_e32 v104, v118
	v_add_f32_e32 v120, v108, v102
	v_sub_f32_e32 v106, v118, v106
	v_sub_f32_e32 v108, v120, v108
	v_mul_f32_e32 v204, v120, v104
	v_sub_f32_e32 v106, v110, v106
	v_mul_f32_e32 v206, v118, v204
	v_sub_f32_e32 v102, v102, v108
	v_fma_f32 v208, v204, v118, -v206
	v_add_f32_e32 v122, v112, v100
	v_fma_f32 v208, v204, v106, v208
	v_mov_b32_e32 v114, v112
	v_add_f32_e32 v210, v206, v208
	v_mov_b32_e32 v124, v100
	v_sub_f32_e32 v212, v120, v210
	v_sub_f32_e32 v206, v210, v206
	v_sub_f32_e32 v120, v120, v212
	v_sub_f32_e32 v206, v206, v208
	v_sub_f32_e32 v120, v120, v210
	s_nop 0
	v_add_f32_e32 v102, v102, v120
	s_nop 0
	v_add_f32_e32 v102, v206, v102
	s_nop 0
	v_add_f32_e32 v120, v212, v102
	v_mov_b32_e32 v116, v122
	v_mul_f32_e32 v206, v104, v120
	v_sub_f32_e32 v208, v212, v120
	v_mul_f32_e32 v210, v118, v206
	v_add_f32_e32 v102, v102, v208
	v_add_f32_e32 v208, v204, v206
	v_fma_f32 v118, v206, v118, -v210
	v_sub_f32_e32 v204, v208, v204
	v_fma_f32 v106, v206, v106, v118
	v_sub_f32_e32 v118, v206, v204
	v_add_f32_e32 v204, v210, v106
	s_nop 0
	v_sub_f32_e32 v206, v204, v210
	v_sub_f32_e32 v210, v120, v204
	v_sub_f32_e32 v106, v206, v106
	v_sub_f32_e32 v120, v120, v210
	v_cmp_neq_f32_e32 vcc, s64, v215
	v_sub_f32_e32 v120, v120, v204
	s_nop 0
	v_add_f32_e32 v102, v102, v120
	s_nop 0
	v_add_f32_e32 v102, v106, v102
	v_min_f32_e32 v64, 0, v64
	v_add_f32_e32 v102, v210, v102
	s_nop 0
	v_mul_f32_e32 v102, v104, v102
	s_nop 0
	v_add_f32_e32 v102, v118, v102
	s_nop 0
	v_add_f32_e32 v104, v208, v102
	s_nop 0
	v_sub_f32_e32 v106, v104, v208
	v_mul_f32_e32 v120, v104, v104
	v_sub_f32_e32 v102, v102, v106
	v_fma_f32 v106, v120, s46, v98
	v_ldexp_f32 v118, v104, 1
	v_mul_f32_e32 v104, v104, v120
	v_fma_f32 v106, v120, v106, s48
	s_nop 0
	v_mul_f32_e32 v104, v104, v106
	v_ldexp_f32 v102, v102, 1
	v_add_f32_e32 v106, v118, v104
	s_nop 0
	v_sub_f32_e32 v118, v106, v118
	v_mov_b32_e32 v110, v106
	v_sub_f32_e32 v104, v104, v118
	s_nop 0
	v_add_f32_e32 v118, v102, v104
	s_nop 0
	v_add_f32_e32 v120, v106, v118
	v_add_f32_e32 v102, v102, v104
	v_add_f32_e32 v104, v122, v120
	v_add_f32_e32 v114, v114, v124
	v_mov_b32_e32 v124, v120
	s_nop 0
	v_sub_f32_e32 v110, v124, v110
	v_mov_b32_e32 v108, v104
	v_mov_b32_e32 v124, v122
	v_mov_b32_e32 v126, v120
	v_sub_f32_e32 v108, v108, v116
	v_sub_f32_e32 v112, v124, v112
	v_sub_f32_e32 v116, v126, v108
	v_mov_b32_e32 v124, v112
	v_mov_b32_e32 v126, v104
	v_sub_f32_e32 v124, v100, v124
	v_sub_f32_e32 v108, v126, v108
	s_nop 0
	v_sub_f32_e32 v108, v114, v108
	v_sub_f32_e32 v100, v100, v112
	v_sub_f32_e32 v102, v102, v110
	v_add_f32_e32 v112, v116, v108
	v_add_f32_e32 v110, v102, v100
	v_add_f32_e32 v102, v100, v102
	v_sub_f32_e32 v106, v120, v106
	v_sub_f32_e32 v102, v102, v124
	v_mov_b32_e32 v108, v110
	v_sub_f32_e32 v106, v118, v106
	v_sub_f32_e32 v108, v108, v102
	v_sub_f32_e32 v102, v106, v102
	v_sub_f32_e32 v100, v100, v108
	s_nop 0
	v_add_f32_e32 v100, v102, v100
	v_add_f32_e32 v102, v112, v110
	s_nop 0
	v_add_f32_e32 v106, v104, v102
	s_nop 0
	v_sub_f32_e32 v104, v106, v104
	s_nop 0
	v_sub_f32_e32 v102, v102, v104
	s_nop 0
	v_add_f32_e32 v100, v100, v102
	s_nop 0
	v_add_f32_e32 v100, v106, v100
	s_nop 0
	v_cndmask_b32_e32 v100, v200, v100, vcc
	v_cmp_ngt_f32_e32 vcc, -1.0, v215
	s_nop 1
	v_cndmask_b32_e32 v100, v201, v100, vcc
	v_cmp_neq_f32_e32 vcc, -1.0, v215
	s_nop 1
	v_cndmask_b32_e32 v100, v202, v100, vcc
	v_cmp_lt_f32_e64 vcc, |v215|, s65
	s_nop 1
	v_cndmask_b32_e32 v100, v100, v215, vcc
	s_nop 0
	v_sub_f32_e32 v64, v64, v100
	s_nop 0
	global_store_dword v233, v64, s[56:57] offset:48
.LBB0_278:
	s_or_b64 exec, exec, s[12:13]
	s_and_b64 vcc, exec, s[10:11]
	v_mov_b32_e32 v64, v240
	s_cbranch_vccnz .LBB0_280
	s_add_u32 s12, s16, s36
	s_addc_u32 s13, s17, s37
.LBB0_280:
	v_lshlrev_b32_e32 v66, 16, v178
	v_and_b32_e32 v67, 0xffff0000, v178
	v_pk_mul_f32 v[66:67], v[64:65], v[66:67] op_sel_hi:[0,1]
	v_and_b32_e32 v103, 0xffff0000, v97
	v_lshlrev_b32_e32 v68, 16, v179
	s_waitcnt lgkmcnt(7)
	v_and_b32_e32 v69, 0xffff0000, v179
	v_cndmask_b32_e64 v70, v32, v66, s[6:7]
	v_lshlrev_b32_e32 v102, 16, v97
	v_mul_f32_e32 v66, v103, v103
	v_and_b32_e32 v107, 0xffff0000, v95
	v_and_b32_e32 v106, 0xffff0000, v94
	v_pk_mul_f32 v[68:69], v[64:65], v[68:69] op_sel_hi:[0,1]
	s_waitcnt lgkmcnt(4)
	v_cndmask_b32_e64 v71, v33, v67, s[6:7]
	s_waitcnt lgkmcnt(1)
	v_and_b32_e32 v79, 0xffff0000, v96
	v_pk_fma_f32 v[98:99], v[102:103], v[102:103], v[66:67] op_sel_hi:[1,1,0]
	v_lshlrev_b32_e32 v105, 16, v95
	v_lshlrev_b32_e32 v104, 16, v94
	v_pk_mul_f32 v[66:67], v[106:107], v[106:107]
	v_cndmask_b32_e64 v73, v35, v69, s[6:7]
	v_cndmask_b32_e64 v72, v34, v68, s[6:7]
	v_lshlrev_b32_e32 v78, 16, v96
	v_pk_fma_f32 v[108:109], v[104:105], v[104:105], v[66:67]
	ds_read_b128 v[66:69], v234
	v_mul_f32_e32 v94, v79, v79
	s_waitcnt lgkmcnt(0)
	v_pk_fma_f32 v[100:101], v[78:79], v[78:79], v[94:95] op_sel_hi:[1,1,0]
	v_lshlrev_b32_e32 v110, 16, v92
	v_and_b32_e32 v111, 0xffff0000, v92
	v_lshlrev_b32_e32 v112, 16, v93
	v_and_b32_e32 v113, 0xffff0000, v93
	v_lshlrev_b32_e32 v115, 16, v90
	v_and_b32_e32 v117, 0xffff0000, v90
	v_lshlrev_b32_e32 v118, 16, v91
	v_and_b32_e32 v119, 0xffff0000, v91
	ds_read_b128 v[90:93], v234 offset:1024
	ds_read_b128 v[94:97], v234 offset:2048
	v_mov_b32_e32 v114, v100
	v_mov_b32_e32 v120, v98
	v_pk_add_f32 v[122:123], v[100:101], v[98:99]
	ds_read_b128 v[98:101], v234 offset:3072
	v_mov_b32_e32 v121, v115
	v_mul_f32_e32 v65, v117, v117
	v_pk_mul_f32 v[120:121], v[114:115], v[120:121]
	v_pk_add_f32 v[108:109], v[108:109], v[108:109] op_sel:[0,1] op_sel_hi:[1,0]
	v_mul_f32_e32 v114, v111, v111
	v_mov_b32_e32 v123, v121
	v_mov_b32_e32 v109, v65
	v_pk_fma_f32 v[120:121], v[110:111], v[110:111], v[114:115] op_sel_hi:[1,1,0]
	v_mul_f32_e32 v114, v113, v113
	v_mul_f32_e32 v77, v118, v118
	v_mul_f32_e32 v116, v119, v119
	v_pk_add_f32 v[108:109], v[122:123], v[108:109]
	v_pk_fma_f32 v[122:123], v[112:113], v[112:113], v[114:115] op_sel_hi:[1,1,0]
	v_mov_b32_e32 v121, v77
	v_mov_b32_e32 v123, v116
	v_pk_add_f32 v[120:121], v[120:121], v[122:123]
	v_lshlrev_b32_e32 v74, 16, v176
	v_pk_add_f32 v[108:109], v[108:109], v[120:121]
	v_and_b32_e32 v75, 0xffff0000, v176
	v_add_f32_e32 v65, v108, v109
	ds_bpermute_b32 v108, v190, v65
	v_lshlrev_b32_e32 v76, 16, v177
	v_and_b32_e32 v77, 0xffff0000, v177
	v_pk_mul_f32 v[76:77], v[64:65], v[76:77] op_sel_hi:[0,1]
	v_pk_mul_f32 v[74:75], v[64:65], v[74:75] op_sel_hi:[0,1]
	s_waitcnt lgkmcnt(0)
	v_add_f32_e32 v65, v65, v108
	v_cndmask_b32_e64 v109, v37, v75, s[6:7]
	ds_bpermute_b32 v75, v191, v65
	v_cndmask_b32_e64 v121, v39, v77, s[6:7]
	v_cndmask_b32_e64 v120, v38, v76, s[6:7]
	v_lshlrev_b32_e32 v76, 16, v175
	v_and_b32_e32 v77, 0xffff0000, v175
	s_waitcnt lgkmcnt(0)
	v_add_f32_e32 v65, v65, v75
	ds_bpermute_b32 v114, v192, v65
	v_pk_mul_f32 v[76:77], v[64:65], v[76:77] op_sel_hi:[0,1]
	v_cndmask_b32_e64 v108, v36, v74, s[6:7]
	v_lshlrev_b32_e32 v74, 16, v174
	v_and_b32_e32 v75, 0xffff0000, v174
	s_waitcnt lgkmcnt(0)
	v_add_f32_e32 v65, v65, v114
	ds_bpermute_b32 v114, v193, v65
	v_pk_mul_f32 v[74:75], v[64:65], v[74:75] op_sel_hi:[0,1]
	v_cndmask_b32_e64 v125, v43, v77, s[6:7]
	v_cndmask_b32_e64 v123, v41, v75, s[6:7]
	v_cndmask_b32_e64 v122, v40, v74, s[6:7]
	s_waitcnt lgkmcnt(0)
	v_add_f32_e32 v65, v65, v114
	ds_bpermute_b32 v77, v194, v65
	v_cndmask_b32_e64 v124, v42, v76, s[6:7]
	v_lshlrev_b32_e32 v74, 16, v172
	v_and_b32_e32 v75, 0xffff0000, v172
	v_lshlrev_b32_e32 v76, 16, v173
	s_waitcnt lgkmcnt(0)
	v_add_f32_e32 v114, v65, v77
	ds_bpermute_b32 v116, v195, v114
	v_and_b32_e32 v77, 0xffff0000, v173
	v_pk_mul_f32 v[76:77], v[64:65], v[76:77] op_sel_hi:[0,1]
	v_pk_mul_f32 v[64:65], v[64:65], v[74:75] op_sel_hi:[0,1]
	v_cndmask_b32_e64 v127, v45, v65, s[6:7]
	s_waitcnt lgkmcnt(0)
	v_add_f32_e32 v65, v114, v116
	v_fmamk_f32 v65, v65, 0x3a800000, v197
	v_mul_f32_e32 v74, 0x4b800000, v65
	v_cmp_gt_f32_e32 vcc, s59, v65
	v_cndmask_b32_e64 v126, v44, v64, s[6:7]
	v_cndmask_b32_e64 v205, v47, v77, s[6:7]
	v_cndmask_b32_e32 v65, v65, v74, vcc
	v_rsq_f32_e32 v65, v65
	v_cndmask_b32_e64 v204, v46, v76, s[6:7]
	v_mov_b32_e32 v116, v115
	v_mul_f32_e32 v64, 0x45800000, v65
	v_cndmask_b32_e32 v64, v65, v64, vcc
	v_mul_f32_e32 v114, 0.5, v64
	v_pk_mul_f32 v[64:65], v[114:115], v[78:79] op_sel_hi:[0,1]
	v_pk_mul_f32 v[74:75], v[114:115], v[102:103] op_sel_hi:[0,1]
	s_waitcnt lgkmcnt(9)
	v_pk_fma_f32 v[76:77], v[66:67], v[64:65], v[70:71]
	v_mov_b32_e32 v64, v104
	v_mov_b32_e32 v65, v106
	v_mov_b32_e32 v106, v105
	v_pk_fma_f32 v[74:75], v[68:69], v[74:75], v[72:73]
	v_pk_mul_f32 v[64:65], v[114:115], v[64:65] op_sel_hi:[0,1]
	v_pk_mul_f32 v[66:67], v[114:115], v[106:107] op_sel_hi:[0,1]
	v_pk_mul_f32 v[78:79], v[118:119], v[114:115] op_sel_hi:[1,0]
	s_waitcnt lgkmcnt(8)
	v_pk_fma_f32 v[70:71], v[92:93], v[66:67], v[120:121]
	v_pk_fma_f32 v[72:73], v[90:91], v[64:65], v[108:109]
	v_pk_mul_f32 v[66:67], v[114:115], v[110:111] op_sel_hi:[0,1]
	s_waitcnt lgkmcnt(6)
	v_pk_fma_f32 v[90:91], v[100:101], v[78:79], v[204:205]
	v_pk_mul_f32 v[78:79], v[74:75], v[74:75]
	v_pk_mul_f32 v[92:93], v[76:77], v[76:77]
	v_pk_fma_f32 v[66:67], v[94:95], v[66:67], v[122:123]
	v_pk_mov_b32 v[94:95], v[92:93], v[78:79] op_sel:[1,0]
	v_mov_b32_e32 v93, v79
	v_pk_add_f32 v[78:79], v[94:95], v[92:93]
	v_pk_mul_f32 v[64:65], v[114:115], v[112:113] op_sel_hi:[0,1]
	v_pk_add_f32 v[78:79], v[78:79], v[78:79] op_sel_hi:[0,1]
	v_pk_mul_f32 v[92:93], v[70:71], v[70:71]
	v_pk_mul_f32 v[94:95], v[72:73], v[72:73]
	v_pk_fma_f32 v[64:65], v[96:97], v[64:65], v[124:125]
	v_pk_mov_b32 v[96:97], v[94:95], v[92:93] op_sel:[1,0]
	v_mov_b32_e32 v95, v93
	v_mul_f32_e32 v78, v66, v66
	v_pk_mul_f32 v[68:69], v[116:117], v[114:115] op_sel_hi:[1,0]
	v_pk_add_f32 v[92:93], v[96:97], v[94:95]
	v_pk_fma_f32 v[94:95], v[66:67], v[66:67], v[78:79] op_sel_hi:[1,1,0]
	v_mul_f32_e32 v78, v64, v64
	v_pk_fma_f32 v[68:69], v[98:99], v[68:69], v[126:127]
	v_pk_add_f32 v[92:93], v[92:93], v[92:93] op_sel_hi:[0,1]
	v_pk_fma_f32 v[96:97], v[64:65], v[64:65], v[78:79] op_sel_hi:[1,1,0]
	v_mul_f32_e32 v94, v68, v68
	v_mul_f32_e32 v96, v69, v69
	v_mul_f32_e32 v78, v90, v90
	v_mul_f32_e32 v92, v91, v91
	v_pk_add_f32 v[94:95], v[94:95], v[96:97]
	v_pk_add_f32 v[78:79], v[78:79], v[92:93]
	s_nop 0
	v_pk_add_f32 v[78:79], v[94:95], v[78:79]
	s_nop 0
	v_add_f32_e32 v78, v78, v79
	ds_bpermute_b32 v79, v190, v78
	s_waitcnt lgkmcnt(0)
	v_add_f32_e32 v78, v78, v79
	ds_bpermute_b32 v79, v191, v78
	s_waitcnt lgkmcnt(0)
	v_add_f32_e32 v78, v78, v79
	ds_bpermute_b32 v79, v192, v78
	s_waitcnt lgkmcnt(0)
	v_add_f32_e32 v78, v78, v79
	ds_bpermute_b32 v79, v193, v78
	s_waitcnt lgkmcnt(0)
	v_add_f32_e32 v78, v78, v79
	ds_bpermute_b32 v79, v194, v78
	s_waitcnt lgkmcnt(0)
	v_add_f32_e32 v78, v78, v79
	ds_bpermute_b32 v79, v195, v78
	s_waitcnt lgkmcnt(0)
	v_add_f32_e32 v78, v78, v79
	v_fmamk_f32 v78, v78, 0x3a800000, v197
	v_mul_f32_e32 v79, 0x4b800000, v78
	v_cmp_gt_f32_e32 vcc, s59, v78
	s_nop 1
	v_cndmask_b32_e32 v79, v78, v79, vcc
	v_rsq_f32_e32 v79, v79
	s_nop 0
	v_mul_f32_e32 v92, 0x45800000, v79
	v_cndmask_b32_e32 v92, v79, v92, vcc
	v_pk_mul_f32 v[94:95], v[74:75], v[92:93] op_sel_hi:[1,0]
	v_pk_mul_f32 v[96:97], v[76:77], v[92:93] op_sel_hi:[1,0]
	v_add_co_u32_e32 v88, vcc, s66, v88
	v_cvt_pk_bf16_f32 v96, v96, v97
	v_cvt_pk_bf16_f32 v97, v94, v95
	v_addc_co_u32_e32 v89, vcc, 0, v89, vcc
	global_store_dwordx2 v[88:89], v[96:97], off
	v_pk_mul_f32 v[94:95], v[70:71], v[92:93] op_sel_hi:[1,0]
	v_pk_mul_f32 v[96:97], v[72:73], v[92:93] op_sel_hi:[1,0]
	s_nop 0
	v_cvt_pk_bf16_f32 v96, v96, v97
	v_cvt_pk_bf16_f32 v97, v94, v95
	global_store_dwordx2 v[88:89], v[96:97], off offset:512
	v_pk_mul_f32 v[94:95], v[64:65], v[92:93] op_sel_hi:[1,0]
	v_pk_mul_f32 v[96:97], v[66:67], v[92:93] op_sel_hi:[1,0]
	s_nop 0
	v_cvt_pk_bf16_f32 v96, v96, v97
	v_cvt_pk_bf16_f32 v97, v94, v95
	global_store_dwordx2 v[88:89], v[96:97], off offset:1024
	v_pk_mul_f32 v[94:95], v[90:91], v[92:93] op_sel_hi:[1,0]
	v_pk_mul_f32 v[96:97], v[68:69], v[92:93] op_sel_hi:[1,0]
	s_nop 0
	v_cvt_pk_bf16_f32 v96, v96, v97
	v_cvt_pk_bf16_f32 v97, v94, v95
	global_store_dwordx2 v[88:89], v[96:97], off offset:1536
	s_and_saveexec_b64 s[56:57], s[4:5]
	s_cbranch_execz .LBB0_282
	v_mul_f32_e32 v79, 0x4f800000, v78
	v_cmp_gt_f32_e32 vcc, s61, v78
	s_nop 1
	v_cndmask_b32_e32 v78, v78, v79, vcc
	v_sqrt_f32_e32 v79, v78
	s_nop 0
	v_add_u32_e32 v88, -1, v79
	v_fma_f32 v93, -v88, v79, v78
	v_add_u32_e32 v89, 1, v79
	v_cmp_ge_f32_e64 s[12:13], 0, v93
	s_nop 1
	v_cndmask_b32_e64 v88, v79, v88, s[12:13]
	v_fma_f32 v79, -v89, v79, v78
	v_cmp_lt_f32_e64 s[12:13], 0, v79
	s_nop 1
	v_cndmask_b32_e64 v79, v88, v89, s[12:13]
	v_mul_f32_e32 v88, 0x37800000, v79
	v_cndmask_b32_e32 v79, v79, v88, vcc
	v_cmp_class_f32_e32 vcc, v78, v198
	s_add_u32 s12, s16, s36
	s_addc_u32 s13, s17, s37
	v_cndmask_b32_e32 v78, v79, v78, vcc
	global_store_dword v196, v78, s[12:13] offset:8
.LBB0_282:
	s_or_b64 exec, exec, s[56:57]
	ds_read_b128 v[94:97], v235
	ds_read_b128 v[98:101], v230 offset:3072
	ds_read_b128 v[102:105], v230 offset:2048
	ds_read_b128 v[106:109], v230 offset:1024
	ds_read_b128 v[110:113], v230
	v_mul_f32_e32 v76, v76, v92
	v_mul_f32_e32 v74, v74, v92
	v_mul_f32_e32 v72, v72, v92
	v_mul_f32_e32 v70, v70, v92
	v_mul_f32_e32 v66, v66, v92
	v_mul_f32_e32 v64, v64, v92
	v_mul_f32_e32 v68, v68, v92
	v_mul_f32_e32 v90, v90, v92
	s_waitcnt lgkmcnt(4)
	v_mul_f32_e32 v76, v76, v94
	v_mul_f32_e32 v74, v74, v96
	s_waitcnt lgkmcnt(1)
	v_pk_fma_f32 v[108:109], v[108:109], v[76:77], 0 op_sel_hi:[1,0,0]
	s_waitcnt lgkmcnt(0)
	v_pk_fma_f32 v[78:79], v[112:113], v[76:77], 0 op_sel_hi:[1,0,0]
	v_pk_fma_f32 v[88:89], v[110:111], v[76:77], 0 op_sel_hi:[1,0,0]
	v_pk_fma_f32 v[106:107], v[106:107], v[76:77], 0 op_sel_hi:[1,0,0]
	v_mul_f32_e32 v76, v77, v92
	v_mul_f32_e32 v76, v76, v95
	v_pk_fma_f32 v[94:95], v[104:105], v[76:77], v[78:79] op_sel_hi:[1,0,1]
	v_pk_fma_f32 v[88:89], v[102:103], v[76:77], v[88:89] op_sel_hi:[1,0,1]
	v_pk_fma_f32 v[110:111], v[76:77], v[100:101], v[108:109] op_sel_hi:[0,1,1]
	v_pk_fma_f32 v[112:113], v[76:77], v[98:99], v[106:107] op_sel_hi:[0,1,1]
	ds_read_b128 v[76:79], v230 offset:19456
	ds_read_b128 v[98:101], v230 offset:18432
	ds_read_b128 v[102:105], v230 offset:17408
	ds_read_b128 v[106:109], v230 offset:16384
	s_waitcnt lgkmcnt(1)
	v_pk_fma_f32 v[102:103], v[74:75], v[102:103], v[112:113] op_sel_hi:[0,1,1]
	s_waitcnt lgkmcnt(0)
	v_pk_fma_f32 v[88:89], v[74:75], v[106:107], v[88:89] op_sel_hi:[0,1,1]
	v_pk_fma_f32 v[94:95], v[74:75], v[108:109], v[94:95] op_sel_hi:[0,1,1]
	v_pk_fma_f32 v[104:105], v[74:75], v[104:105], v[110:111] op_sel_hi:[0,1,1]
	v_mul_f32_e32 v74, v75, v92
	v_mul_f32_e32 v74, v74, v97
	v_pk_fma_f32 v[110:111], v[74:75], v[100:101], v[94:95] op_sel_hi:[0,1,1]
	v_pk_fma_f32 v[88:89], v[74:75], v[98:99], v[88:89] op_sel_hi:[0,1,1]
	v_pk_fma_f32 v[78:79], v[74:75], v[78:79], v[104:105] op_sel_hi:[0,1,1]
	v_pk_fma_f32 v[112:113], v[74:75], v[76:77], v[102:103] op_sel_hi:[0,1,1]
	ds_read_b128 v[74:77], v235 offset:1024
	ds_read_b128 v[94:97], v230 offset:35840
	ds_read_b128 v[98:101], v230 offset:34816
	ds_read_b128 v[102:105], v230 offset:33792
	ds_read_b128 v[106:109], v230 offset:32768
	s_waitcnt lgkmcnt(4)
	v_mul_f32_e32 v72, v72, v74
	v_mul_f32_e32 v70, v70, v76
	s_waitcnt lgkmcnt(1)
	v_pk_fma_f32 v[102:103], v[102:103], v[72:73], v[112:113] op_sel_hi:[1,0,1]
	s_waitcnt lgkmcnt(0)
	v_pk_fma_f32 v[88:89], v[106:107], v[72:73], v[88:89] op_sel_hi:[1,0,1]
	v_pk_fma_f32 v[106:107], v[108:109], v[72:73], v[110:111] op_sel_hi:[1,0,1]
	v_pk_fma_f32 v[78:79], v[104:105], v[72:73], v[78:79] op_sel_hi:[1,0,1]
	v_mul_f32_e32 v72, v73, v92
	v_mul_f32_e32 v72, v72, v75
	v_pk_fma_f32 v[106:107], v[100:101], v[72:73], v[106:107] op_sel_hi:[1,0,1]
	v_pk_fma_f32 v[88:89], v[98:99], v[72:73], v[88:89] op_sel_hi:[1,0,1]
	v_pk_fma_f32 v[78:79], v[72:73], v[96:97], v[78:79] op_sel_hi:[0,1,1]
	v_pk_fma_f32 v[108:109], v[72:73], v[94:95], v[102:103] op_sel_hi:[0,1,1]
	ds_read_b128 v[72:75], v230 offset:52224
	ds_read_b128 v[94:97], v230 offset:51200
	ds_read_b128 v[98:101], v230 offset:50176
	ds_read_b128 v[102:105], v230 offset:49152
	s_waitcnt lgkmcnt(1)
	v_pk_fma_f32 v[98:99], v[70:71], v[98:99], v[108:109] op_sel_hi:[0,1,1]
	s_waitcnt lgkmcnt(0)
	v_pk_fma_f32 v[88:89], v[70:71], v[102:103], v[88:89] op_sel_hi:[0,1,1]
	v_pk_fma_f32 v[102:103], v[70:71], v[104:105], v[106:107] op_sel_hi:[0,1,1]
	v_pk_fma_f32 v[78:79], v[70:71], v[100:101], v[78:79] op_sel_hi:[0,1,1]
	v_mul_f32_e32 v70, v71, v92
	v_mul_f32_e32 v70, v70, v77
	v_pk_fma_f32 v[106:107], v[70:71], v[96:97], v[102:103] op_sel_hi:[0,1,1]
	v_pk_fma_f32 v[88:89], v[70:71], v[94:95], v[88:89] op_sel_hi:[0,1,1]
	v_pk_fma_f32 v[78:79], v[70:71], v[74:75], v[78:79] op_sel_hi:[0,1,1]
	v_pk_fma_f32 v[108:109], v[70:71], v[72:73], v[98:99] op_sel_hi:[0,1,1]
	ds_read_b128 v[70:73], v235 offset:2048
	ds_read_b128 v[74:77], v231 offset:3072
	ds_read_b128 v[94:97], v231 offset:2048
	ds_read_b128 v[98:101], v231 offset:1024
	ds_read_b128 v[102:105], v231
	s_waitcnt lgkmcnt(4)
	v_mul_f32_e32 v66, v66, v70
	v_mul_f32_e32 v64, v64, v72
	s_waitcnt lgkmcnt(1)
	v_pk_fma_f32 v[98:99], v[98:99], v[66:67], v[108:109] op_sel_hi:[1,0,1]
	s_waitcnt lgkmcnt(0)
	v_pk_fma_f32 v[88:89], v[102:103], v[66:67], v[88:89] op_sel_hi:[1,0,1]
	v_pk_fma_f32 v[102:103], v[104:105], v[66:67], v[106:107] op_sel_hi:[1,0,1]
	v_pk_fma_f32 v[78:79], v[100:101], v[66:67], v[78:79] op_sel_hi:[1,0,1]
	v_mul_f32_e32 v66, v67, v92
	v_mul_f32_e32 v66, v66, v71
	v_pk_fma_f32 v[70:71], v[96:97], v[66:67], v[102:103] op_sel_hi:[1,0,1]
	v_pk_fma_f32 v[88:89], v[94:95], v[66:67], v[88:89] op_sel_hi:[1,0,1]
	v_pk_fma_f32 v[78:79], v[66:67], v[76:77], v[78:79] op_sel_hi:[0,1,1]
	v_pk_fma_f32 v[66:67], v[66:67], v[74:75], v[98:99] op_sel_hi:[0,1,1]
	ds_read_b128 v[74:77], v231 offset:19456
	ds_read_b128 v[94:97], v231 offset:18432
	ds_read_b128 v[98:101], v231 offset:17408
	ds_read_b128 v[102:105], v231 offset:16384
	s_waitcnt lgkmcnt(1)
	v_pk_fma_f32 v[66:67], v[64:65], v[98:99], v[66:67] op_sel_hi:[0,1,1]
	s_waitcnt lgkmcnt(0)
	v_pk_fma_f32 v[88:89], v[64:65], v[102:103], v[88:89] op_sel_hi:[0,1,1]
	v_pk_fma_f32 v[70:71], v[64:65], v[104:105], v[70:71] op_sel_hi:[0,1,1]
	v_pk_fma_f32 v[78:79], v[64:65], v[100:101], v[78:79] op_sel_hi:[0,1,1]
	v_mul_f32_e32 v64, v65, v92
	v_mul_f32_e32 v64, v64, v73
	v_pk_fma_f32 v[102:103], v[64:65], v[96:97], v[70:71] op_sel_hi:[0,1,1]
	v_pk_fma_f32 v[88:89], v[64:65], v[94:95], v[88:89] op_sel_hi:[0,1,1]
	v_pk_fma_f32 v[78:79], v[64:65], v[76:77], v[78:79] op_sel_hi:[0,1,1]
	v_pk_fma_f32 v[104:105], v[64:65], v[74:75], v[66:67] op_sel_hi:[0,1,1]
	ds_read_b128 v[64:67], v235 offset:3072
	ds_read_b128 v[70:73], v231 offset:35840
	ds_read_b128 v[74:77], v231 offset:34816
	ds_read_b128 v[94:97], v231 offset:33792
	ds_read_b128 v[98:101], v231 offset:32768
	s_waitcnt lgkmcnt(4)
	v_mul_f32_e32 v64, v68, v64
	v_mul_f32_e32 v66, v90, v66
	s_waitcnt lgkmcnt(1)
	v_pk_fma_f32 v[78:79], v[96:97], v[64:65], v[78:79] op_sel_hi:[1,0,1]
	s_waitcnt lgkmcnt(0)
	v_pk_fma_f32 v[88:89], v[98:99], v[64:65], v[88:89] op_sel_hi:[1,0,1]
	v_pk_fma_f32 v[98:99], v[100:101], v[64:65], v[102:103] op_sel_hi:[1,0,1]
	v_pk_fma_f32 v[100:101], v[94:95], v[64:65], v[104:105] op_sel_hi:[1,0,1]
	v_mul_f32_e32 v64, v69, v92
	v_mul_f32_e32 v68, v64, v65
	v_pk_fma_f32 v[94:95], v[76:77], v[68:69], v[98:99] op_sel_hi:[1,0,1]
	v_pk_fma_f32 v[96:97], v[74:75], v[68:69], v[88:89] op_sel_hi:[1,0,1]
	v_pk_fma_f32 v[64:65], v[68:69], v[72:73], v[78:79] op_sel_hi:[0,1,1]
	v_pk_fma_f32 v[88:89], v[68:69], v[70:71], v[100:101] op_sel_hi:[0,1,1]
	ds_read_b128 v[68:71], v231 offset:52224
	ds_read_b128 v[72:75], v231 offset:51200
	ds_read_b128 v[76:79], v231 offset:50176
	ds_read_b128 v[98:101], v231 offset:49152
	s_waitcnt lgkmcnt(1)
	v_pk_fma_f32 v[76:77], v[66:67], v[76:77], v[88:89] op_sel_hi:[0,1,1]
	s_waitcnt lgkmcnt(0)
	v_pk_fma_f32 v[96:97], v[66:67], v[98:99], v[96:97] op_sel_hi:[0,1,1]
	v_pk_fma_f32 v[94:95], v[66:67], v[100:101], v[94:95] op_sel_hi:[0,1,1]
	v_pk_fma_f32 v[64:65], v[66:67], v[78:79], v[64:65] op_sel_hi:[0,1,1]
	v_mul_f32_e32 v66, v91, v92
	v_mul_f32_e32 v78, v66, v67
	v_pk_fma_f32 v[64:65], v[78:79], v[70:71], v[64:65] op_sel_hi:[0,1,1]
	v_pk_fma_f32 v[70:71], v[78:79], v[68:69], v[76:77] op_sel_hi:[0,1,1]
	ds_bpermute_b32 v77, v190, v64
	ds_bpermute_b32 v68, v190, v70
	v_pk_fma_f32 v[66:67], v[78:79], v[74:75], v[94:95] op_sel_hi:[0,1,1]
	v_pk_fma_f32 v[72:73], v[78:79], v[72:73], v[96:97] op_sel_hi:[0,1,1]
	ds_bpermute_b32 v74, v190, v72
	s_waitcnt lgkmcnt(2)
	v_add_f32_e32 v64, v64, v77
	ds_bpermute_b32 v77, v191, v64
	s_waitcnt lgkmcnt(2)
	v_add_f32_e32 v68, v70, v68
	ds_bpermute_b32 v75, v190, v73
	ds_bpermute_b32 v70, v190, v71
	ds_bpermute_b32 v76, v190, v66
	s_waitcnt lgkmcnt(3)
	v_add_f32_e32 v64, v64, v77
	ds_bpermute_b32 v77, v192, v64
	s_waitcnt lgkmcnt(3)
	v_pk_add_f32 v[72:73], v[72:73], v[74:75]
	s_waitcnt lgkmcnt(2)
	v_add_f32_e32 v70, v71, v70
	ds_bpermute_b32 v69, v191, v68
	ds_bpermute_b32 v74, v191, v72
	s_waitcnt lgkmcnt(2)
	v_add_f32_e32 v64, v64, v77
	ds_bpermute_b32 v77, v193, v64
	ds_bpermute_b32 v75, v191, v73
	ds_bpermute_b32 v71, v191, v70
	s_waitcnt lgkmcnt(4)
	v_add_f32_e32 v68, v68, v69
	ds_bpermute_b32 v69, v192, v68
	s_waitcnt lgkmcnt(3)
	v_add_f32_e32 v64, v64, v77
	ds_bpermute_b32 v77, v194, v64
	s_waitcnt lgkmcnt(3)
	v_pk_add_f32 v[72:73], v[72:73], v[74:75]
	s_waitcnt lgkmcnt(2)
	v_add_f32_e32 v70, v70, v71
	ds_bpermute_b32 v74, v192, v72
	ds_bpermute_b32 v75, v192, v73
	s_waitcnt lgkmcnt(2)
	v_add_f32_e32 v88, v64, v77
	ds_bpermute_b32 v77, v190, v67
	ds_bpermute_b32 v64, v190, v65
	ds_bpermute_b32 v71, v192, v70
	v_add_f32_e32 v68, v68, v69
	s_waitcnt lgkmcnt(3)
	v_pk_add_f32 v[72:73], v[72:73], v[74:75]
	s_waitcnt lgkmcnt(2)
	v_pk_add_f32 v[66:67], v[66:67], v[76:77]
	s_waitcnt lgkmcnt(1)
	v_add_f32_e32 v64, v65, v64
	ds_bpermute_b32 v76, v191, v66
	ds_bpermute_b32 v77, v191, v67
	ds_bpermute_b32 v65, v191, v64
	s_waitcnt lgkmcnt(3)
	v_add_f32_e32 v70, v70, v71
	ds_bpermute_b32 v69, v193, v68
	ds_bpermute_b32 v74, v193, v72
	s_waitcnt lgkmcnt(3)
	v_pk_add_f32 v[66:67], v[66:67], v[76:77]
	s_waitcnt lgkmcnt(2)
	v_add_f32_e32 v64, v64, v65
	ds_bpermute_b32 v76, v192, v66
	ds_bpermute_b32 v77, v192, v67
	ds_bpermute_b32 v65, v192, v64
	ds_bpermute_b32 v75, v193, v73
	ds_bpermute_b32 v71, v193, v70
	s_waitcnt lgkmcnt(6)
	v_add_f32_e32 v68, v68, v69
	s_waitcnt lgkmcnt(3)
	v_pk_add_f32 v[66:67], v[66:67], v[76:77]
	s_waitcnt lgkmcnt(2)
	v_add_f32_e32 v64, v64, v65
	ds_bpermute_b32 v76, v193, v66
	ds_bpermute_b32 v77, v193, v67
	ds_bpermute_b32 v65, v193, v64
	s_waitcnt lgkmcnt(4)
	v_pk_add_f32 v[72:73], v[72:73], v[74:75]
	s_waitcnt lgkmcnt(3)
	v_add_f32_e32 v70, v70, v71
	ds_bpermute_b32 v69, v194, v68
	s_waitcnt lgkmcnt(2)
	v_pk_add_f32 v[66:67], v[66:67], v[76:77]
	s_waitcnt lgkmcnt(1)
	v_add_f32_e32 v64, v64, v65
	ds_bpermute_b32 v74, v194, v72
	ds_bpermute_b32 v75, v194, v73
	ds_bpermute_b32 v71, v194, v70
	ds_bpermute_b32 v76, v194, v66
	ds_bpermute_b32 v77, v194, v67
	ds_bpermute_b32 v65, v194, v64
	s_waitcnt lgkmcnt(6)
	v_add_f32_e32 v68, v68, v69
	s_waitcnt lgkmcnt(4)
	v_pk_add_f32 v[72:73], v[72:73], v[74:75]
	s_waitcnt lgkmcnt(3)
	v_add_f32_e32 v70, v70, v71
	s_waitcnt lgkmcnt(1)
	v_pk_add_f32 v[76:77], v[66:67], v[76:77]
	s_waitcnt lgkmcnt(0)
	v_add_f32_e32 v90, v64, v65
	ds_bpermute_b32 v69, v195, v68
	ds_bpermute_b32 v74, v195, v72
	ds_bpermute_b32 v75, v195, v73
	ds_bpermute_b32 v71, v195, v70
	ds_bpermute_b32 v89, v195, v88
	ds_bpermute_b32 v78, v195, v76
	ds_bpermute_b32 v79, v195, v77
	ds_bpermute_b32 v91, v195, v90
	s_and_saveexec_b64 s[12:13], 15
	s_cbranch_execz .LBB0_284
	s_waitcnt lgkmcnt(0)
	v_add_f32_e32 v203, v90, v91
	v_add_f32_e32 v90, v68, v69
	v_add_f32_e32 v91, v70, v71
	v_add_f32_e32 v204, v88, v89
	v_mov_b64_e32 v[88:89], s[44:45]
	v_pk_add_f32 v[72:73], v[72:73], v[74:75]
	v_pk_add_f32 v[76:77], v[76:77], v[78:79]
	s_add_u32 s56, s16, s40
	s_addc_u32 s57, s17, s41
	v_mov_b32_e32 v64, v90
	v_mov_b32_e32 v65, v72
	s_mov_b64 vcc, 2
	v_cndmask_b32_e32 v64, v64, v91, vcc
	v_cndmask_b32_e32 v65, v65, v73, vcc
	s_mov_b64 vcc, 4
	v_cndmask_b32_e32 v64, v64, v204, vcc
	v_cndmask_b32_e32 v65, v65, v76, vcc
	s_mov_b64 vcc, 8
	v_cndmask_b32_e32 v64, v64, v203, vcc
	v_cndmask_b32_e32 v65, v65, v77, vcc
	v_add_f32_e32 v64, v64, v236
	v_add_f32_e32 v65, v65, v237
	global_store_dword v233, v65, s[56:57] offset:64
	s_nop 0
	v_mul_f32_e64 v90, |v64|, s62
	s_nop 0
	v_exp_f32_e32 v205, v90
	s_nop 0
	v_add_f32_e32 v94, 1.0, v205
	s_nop 0
	v_frexp_mant_f32_e32 v97, v94
	v_cvt_f64_f32_e32 v[90:91], v94
	s_nop 0
	v_frexp_exp_i32_f64_e32 v90, v[90:91]
	v_cmp_gt_f32_e32 vcc, s63, v97
	v_add_f32_e32 v96, -1.0, v94
	s_nop 0
	v_subbrev_co_u32_e32 v90, vcc, 0, v90, vcc
	v_sub_f32_e32 v100, v96, v94
	v_sub_f32_e32 v96, v205, v96
	v_add_f32_e32 v93, 1.0, v100
	s_nop 0
	v_add_f32_e32 v93, v96, v93
	v_sub_u32_e32 v96, 0, v90
	v_cvt_f32_i32_e32 v90, v90
	v_ldexp_f32 v92, v94, v96
	v_ldexp_f32 v94, v93, v96
	v_add_f32_e32 v96, 1.0, v92
	v_add_f32_e32 v98, -1.0, v92
	v_add_f32_e32 v100, -1.0, v96
	v_add_f32_e32 v102, 1.0, v98
	v_sub_f32_e32 v100, v92, v100
	v_sub_f32_e32 v92, v92, v102
	v_mul_f32_e32 v102, s50, v90
	v_add_f32_e32 v100, v94, v100
	v_add_f32_e32 v92, v94, v92
	v_fma_f32 v94, v90, s50, -v102
	v_add_f32_e32 v108, v96, v100
	v_fma_f32 v90, v90, s52, v94
	v_rcp_f32_e32 v94, v108
	v_add_f32_e32 v110, v98, v92
	v_sub_f32_e32 v96, v108, v96
	v_sub_f32_e32 v98, v110, v98
	v_mul_f32_e32 v118, v110, v94
	v_sub_f32_e32 v96, v100, v96
	v_mul_f32_e32 v120, v108, v118
	v_sub_f32_e32 v92, v92, v98
	v_fma_f32 v122, v118, v108, -v120
	v_add_f32_e32 v112, v102, v90
	v_fma_f32 v122, v118, v96, v122
	v_mov_b32_e32 v104, v102
	v_add_f32_e32 v124, v120, v122
	v_mov_b32_e32 v114, v90
	v_sub_f32_e32 v126, v110, v124
	v_sub_f32_e32 v120, v124, v120
	v_sub_f32_e32 v110, v110, v126
	v_sub_f32_e32 v120, v120, v122
	v_sub_f32_e32 v110, v110, v124
	s_nop 0
	v_add_f32_e32 v92, v92, v110
	s_nop 0
	v_add_f32_e32 v92, v120, v92
	s_nop 0
	v_add_f32_e32 v110, v126, v92
	v_mov_b32_e32 v106, v112
	v_mul_f32_e32 v120, v94, v110
	v_sub_f32_e32 v122, v126, v110
	v_mul_f32_e32 v124, v108, v120
	v_add_f32_e32 v92, v92, v122
	v_add_f32_e32 v122, v118, v120
	v_fma_f32 v108, v120, v108, -v124
	v_sub_f32_e32 v118, v122, v118
	v_fma_f32 v96, v120, v96, v108
	v_sub_f32_e32 v108, v120, v118
	v_add_f32_e32 v118, v124, v96
	s_nop 0
	v_sub_f32_e32 v120, v118, v124
	v_sub_f32_e32 v124, v110, v118
	v_sub_f32_e32 v96, v120, v96
	v_sub_f32_e32 v110, v110, v124
	v_cmp_neq_f32_e32 vcc, s64, v205
	v_sub_f32_e32 v110, v110, v118
	s_nop 0
	v_add_f32_e32 v92, v92, v110
	s_nop 0
	v_add_f32_e32 v92, v96, v92
	v_min_f32_e32 v64, 0, v64
	v_add_f32_e32 v92, v124, v92
	s_nop 0
	v_mul_f32_e32 v92, v94, v92
	s_nop 0
	v_add_f32_e32 v92, v108, v92
	s_nop 0
	v_add_f32_e32 v94, v122, v92
	s_nop 0
	v_sub_f32_e32 v96, v94, v122
	v_mul_f32_e32 v110, v94, v94
	v_sub_f32_e32 v92, v92, v96
	v_fma_f32 v96, v110, s46, v88
	v_ldexp_f32 v108, v94, 1
	v_mul_f32_e32 v94, v94, v110
	v_fma_f32 v96, v110, v96, s48
	s_nop 0
	v_mul_f32_e32 v94, v94, v96
	v_ldexp_f32 v92, v92, 1
	v_add_f32_e32 v96, v108, v94
	s_nop 0
	v_sub_f32_e32 v108, v96, v108
	v_mov_b32_e32 v100, v96
	v_sub_f32_e32 v94, v94, v108
	s_nop 0
	v_add_f32_e32 v108, v92, v94
	s_nop 0
	v_add_f32_e32 v110, v96, v108
	v_add_f32_e32 v92, v92, v94
	v_add_f32_e32 v94, v112, v110
	v_add_f32_e32 v104, v104, v114
	v_mov_b32_e32 v114, v110
	s_nop 0
	v_sub_f32_e32 v100, v114, v100
	v_mov_b32_e32 v98, v94
	v_mov_b32_e32 v114, v112
	v_mov_b32_e32 v116, v110
	v_sub_f32_e32 v98, v98, v106
	v_sub_f32_e32 v102, v114, v102
	v_sub_f32_e32 v106, v116, v98
	v_mov_b32_e32 v114, v102
	v_mov_b32_e32 v116, v94
	v_sub_f32_e32 v114, v90, v114
	v_sub_f32_e32 v98, v116, v98
	s_nop 0
	v_sub_f32_e32 v98, v104, v98
	v_sub_f32_e32 v90, v90, v102
	v_sub_f32_e32 v92, v92, v100
	v_add_f32_e32 v102, v106, v98
	v_add_f32_e32 v100, v92, v90
	v_add_f32_e32 v92, v90, v92
	v_sub_f32_e32 v96, v110, v96
	v_sub_f32_e32 v92, v92, v114
	v_mov_b32_e32 v98, v100
	v_sub_f32_e32 v96, v108, v96
	v_sub_f32_e32 v98, v98, v92
	v_sub_f32_e32 v92, v96, v92
	v_sub_f32_e32 v90, v90, v98
	s_nop 0
	v_add_f32_e32 v90, v92, v90
	v_add_f32_e32 v92, v102, v100
	s_nop 0
	v_add_f32_e32 v96, v94, v92
	s_nop 0
	v_sub_f32_e32 v94, v96, v94
	s_nop 0
	v_sub_f32_e32 v92, v92, v94
	s_nop 0
	v_add_f32_e32 v90, v90, v92
	s_nop 0
	v_add_f32_e32 v90, v96, v90
	s_nop 0
	v_cndmask_b32_e32 v90, v200, v90, vcc
	v_cmp_ngt_f32_e32 vcc, -1.0, v205
	s_nop 1
	v_cndmask_b32_e32 v90, v201, v90, vcc
	v_cmp_neq_f32_e32 vcc, -1.0, v205
	s_nop 1
	v_cndmask_b32_e32 v90, v202, v90, vcc
	v_cmp_lt_f32_e64 vcc, |v205|, s65
	s_nop 1
	v_cndmask_b32_e32 v90, v90, v205, vcc
	s_nop 0
	v_sub_f32_e32 v64, v64, v90
	s_nop 0
	global_store_dword v233, v64, s[56:57] offset:80
.LBB0_284:
	s_or_b64 exec, exec, s[12:13]
	s_and_b64 vcc, exec, s[10:11]
	v_mov_b32_e32 v64, v241
	s_cbranch_vccnz .LBB0_286
	s_lshl_b64 s[10:11], s[54:55], 2
	s_add_u32 s10, s49, s10
	s_addc_u32 s11, s51, s11
.LBB0_286:
	v_lshlrev_b32_e32 v66, 16, v186
	v_and_b32_e32 v67, 0xffff0000, v186
	v_pk_mul_f32 v[66:67], v[64:65], v[66:67] op_sel_hi:[0,1]
	v_and_b32_e32 v93, 0xffff0000, v87
	v_lshlrev_b32_e32 v68, 16, v187
	s_waitcnt lgkmcnt(7)
	v_and_b32_e32 v69, 0xffff0000, v187
	v_cndmask_b32_e64 v70, v48, v66, s[6:7]
	v_lshlrev_b32_e32 v92, 16, v87
	v_mul_f32_e32 v66, v93, v93
	v_and_b32_e32 v97, 0xffff0000, v85
	v_and_b32_e32 v96, 0xffff0000, v84
	v_pk_mul_f32 v[68:69], v[64:65], v[68:69] op_sel_hi:[0,1]
	s_waitcnt lgkmcnt(4)
	v_cndmask_b32_e64 v71, v49, v67, s[6:7]
	v_lshlrev_b32_e32 v90, 16, v86
	s_waitcnt lgkmcnt(0)
	v_and_b32_e32 v91, 0xffff0000, v86
	v_pk_fma_f32 v[86:87], v[92:93], v[92:93], v[66:67] op_sel_hi:[1,1,0]
	v_lshlrev_b32_e32 v95, 16, v85
	v_lshlrev_b32_e32 v94, 16, v84
	v_pk_mul_f32 v[66:67], v[96:97], v[96:97]
	v_cndmask_b32_e64 v73, v51, v69, s[6:7]
	v_cndmask_b32_e64 v72, v50, v68, s[6:7]
	v_pk_fma_f32 v[98:99], v[94:95], v[94:95], v[66:67]
	ds_read_b128 v[66:69], v234
	v_lshlrev_b32_e32 v100, 16, v82
	v_and_b32_e32 v101, 0xffff0000, v82
	v_mul_f32_e32 v82, v91, v91
	v_lshlrev_b32_e32 v105, 16, v80
	v_and_b32_e32 v107, 0xffff0000, v80
	v_lshlrev_b32_e32 v108, 16, v81
	v_and_b32_e32 v109, 0xffff0000, v81
	ds_read_b128 v[78:81], v234 offset:1024
	v_pk_fma_f32 v[88:89], v[90:91], v[90:91], v[82:83] op_sel_hi:[1,1,0]
	v_lshlrev_b32_e32 v102, 16, v83
	v_and_b32_e32 v103, 0xffff0000, v83
	ds_read_b128 v[82:85], v234 offset:2048
	v_mov_b32_e32 v104, v88
	v_mov_b32_e32 v110, v86
	v_pk_add_f32 v[112:113], v[88:89], v[86:87]
	ds_read_b128 v[86:89], v234 offset:3072
	v_mov_b32_e32 v111, v105
	v_mul_f32_e32 v65, v107, v107
	v_pk_mul_f32 v[110:111], v[104:105], v[110:111]
	v_pk_add_f32 v[98:99], v[98:99], v[98:99] op_sel:[0,1] op_sel_hi:[1,0]
	v_mul_f32_e32 v104, v101, v101
	v_mov_b32_e32 v113, v111
	v_mov_b32_e32 v99, v65
	v_pk_fma_f32 v[110:111], v[100:101], v[100:101], v[104:105] op_sel_hi:[1,1,0]
	v_mul_f32_e32 v104, v103, v103
	v_mul_f32_e32 v77, v108, v108
	v_mul_f32_e32 v106, v109, v109
	v_pk_add_f32 v[98:99], v[112:113], v[98:99]
	v_pk_fma_f32 v[112:113], v[102:103], v[102:103], v[104:105] op_sel_hi:[1,1,0]
	v_mov_b32_e32 v111, v77
	v_mov_b32_e32 v113, v106
	v_pk_add_f32 v[110:111], v[110:111], v[112:113]
	v_lshlrev_b32_e32 v74, 16, v184
	v_pk_add_f32 v[98:99], v[98:99], v[110:111]
	v_and_b32_e32 v75, 0xffff0000, v184
	v_add_f32_e32 v65, v98, v99
	ds_bpermute_b32 v98, v190, v65
	v_lshlrev_b32_e32 v76, 16, v185
	v_and_b32_e32 v77, 0xffff0000, v185
	v_pk_mul_f32 v[76:77], v[64:65], v[76:77] op_sel_hi:[0,1]
	v_pk_mul_f32 v[74:75], v[64:65], v[74:75] op_sel_hi:[0,1]
	s_waitcnt lgkmcnt(0)
	v_add_f32_e32 v65, v65, v98
	v_cndmask_b32_e64 v99, v53, v75, s[6:7]
	ds_bpermute_b32 v75, v191, v65
	v_cndmask_b32_e64 v111, v55, v77, s[6:7]
	v_cndmask_b32_e64 v110, v54, v76, s[6:7]
	v_lshlrev_b32_e32 v76, 16, v183
	v_and_b32_e32 v77, 0xffff0000, v183
	s_waitcnt lgkmcnt(0)
	v_add_f32_e32 v65, v65, v75
	ds_bpermute_b32 v104, v192, v65
	v_pk_mul_f32 v[76:77], v[64:65], v[76:77] op_sel_hi:[0,1]
	v_cndmask_b32_e64 v98, v52, v74, s[6:7]
	v_lshlrev_b32_e32 v74, 16, v182
	v_and_b32_e32 v75, 0xffff0000, v182
	s_waitcnt lgkmcnt(0)
	v_add_f32_e32 v65, v65, v104
	ds_bpermute_b32 v104, v193, v65
	v_pk_mul_f32 v[74:75], v[64:65], v[74:75] op_sel_hi:[0,1]
	v_cndmask_b32_e64 v115, v59, v77, s[6:7]
	v_cndmask_b32_e64 v113, v57, v75, s[6:7]
	v_cndmask_b32_e64 v112, v56, v74, s[6:7]
	s_waitcnt lgkmcnt(0)
	v_add_f32_e32 v65, v65, v104
	ds_bpermute_b32 v77, v194, v65
	v_cndmask_b32_e64 v114, v58, v76, s[6:7]
	v_lshlrev_b32_e32 v74, 16, v180
	v_and_b32_e32 v75, 0xffff0000, v180
	v_lshlrev_b32_e32 v76, 16, v181
	s_waitcnt lgkmcnt(0)
	v_add_f32_e32 v104, v65, v77
	ds_bpermute_b32 v106, v195, v104
	v_and_b32_e32 v77, 0xffff0000, v181
	v_pk_mul_f32 v[76:77], v[64:65], v[76:77] op_sel_hi:[0,1]
	v_pk_mul_f32 v[64:65], v[64:65], v[74:75] op_sel_hi:[0,1]
	v_cndmask_b32_e64 v117, v61, v65, s[6:7]
	s_waitcnt lgkmcnt(0)
	v_add_f32_e32 v65, v104, v106
	v_fmamk_f32 v65, v65, 0x3a800000, v197
	v_mul_f32_e32 v74, 0x4b800000, v65
	v_cmp_gt_f32_e32 vcc, s59, v65
	v_cndmask_b32_e64 v116, v60, v64, s[6:7]
	v_cndmask_b32_e64 v119, v63, v77, s[6:7]
	v_cndmask_b32_e32 v65, v65, v74, vcc
	v_rsq_f32_e32 v65, v65
	v_cndmask_b32_e64 v118, v62, v76, s[6:7]
	v_mov_b32_e32 v106, v105
	v_mul_f32_e32 v64, 0x45800000, v65
	v_cndmask_b32_e32 v64, v65, v64, vcc
	v_mul_f32_e32 v104, 0.5, v64
	v_pk_mul_f32 v[64:65], v[104:105], v[90:91] op_sel_hi:[0,1]
	s_waitcnt lgkmcnt(9)
	v_pk_fma_f32 v[76:77], v[66:67], v[64:65], v[70:71]
	v_mov_b32_e32 v64, v94
	v_mov_b32_e32 v65, v96
	v_mov_b32_e32 v96, v95
	v_pk_mul_f32 v[74:75], v[104:105], v[92:93] op_sel_hi:[0,1]
	v_pk_mul_f32 v[64:65], v[104:105], v[64:65] op_sel_hi:[0,1]
	v_pk_mul_f32 v[66:67], v[104:105], v[96:97] op_sel_hi:[0,1]
	v_pk_fma_f32 v[74:75], v[68:69], v[74:75], v[72:73]
	s_waitcnt lgkmcnt(8)
	v_pk_fma_f32 v[70:71], v[80:81], v[66:67], v[110:111]
	v_pk_fma_f32 v[72:73], v[78:79], v[64:65], v[98:99]
	v_pk_mul_f32 v[66:67], v[104:105], v[100:101] op_sel_hi:[0,1]
	v_pk_mul_f32 v[78:79], v[108:109], v[104:105] op_sel_hi:[1,0]
	v_pk_mul_f32 v[64:65], v[104:105], v[102:103] op_sel_hi:[0,1]
	s_waitcnt lgkmcnt(7)
	v_pk_fma_f32 v[66:67], v[82:83], v[66:67], v[112:113]
	s_waitcnt lgkmcnt(6)
	v_pk_fma_f32 v[80:81], v[88:89], v[78:79], v[118:119]
	v_pk_mul_f32 v[78:79], v[74:75], v[74:75]
	v_pk_mul_f32 v[82:83], v[76:77], v[76:77]
	v_pk_fma_f32 v[64:65], v[84:85], v[64:65], v[114:115]
	v_pk_mov_b32 v[84:85], v[82:83], v[78:79] op_sel:[1,0]
	v_mov_b32_e32 v83, v79
	v_pk_add_f32 v[78:79], v[84:85], v[82:83]
	v_pk_mul_f32 v[68:69], v[106:107], v[104:105] op_sel_hi:[1,0]
	v_pk_add_f32 v[78:79], v[78:79], v[78:79] op_sel_hi:[0,1]
	v_pk_mul_f32 v[82:83], v[70:71], v[70:71]
	v_pk_mul_f32 v[84:85], v[72:73], v[72:73]
	v_pk_fma_f32 v[68:69], v[86:87], v[68:69], v[116:117]
	v_pk_mov_b32 v[86:87], v[84:85], v[82:83] op_sel:[1,0]
	v_mov_b32_e32 v85, v83
	v_mul_f32_e32 v78, v66, v66
	v_pk_add_f32 v[82:83], v[86:87], v[84:85]
	v_pk_fma_f32 v[84:85], v[66:67], v[66:67], v[78:79] op_sel_hi:[1,1,0]
	v_mul_f32_e32 v78, v64, v64
	v_pk_add_f32 v[82:83], v[82:83], v[82:83] op_sel_hi:[0,1]
	v_pk_fma_f32 v[86:87], v[64:65], v[64:65], v[78:79] op_sel_hi:[1,1,0]
	v_mul_f32_e32 v84, v68, v68
	v_mul_f32_e32 v86, v69, v69
	v_mul_f32_e32 v78, v80, v80
	v_mul_f32_e32 v82, v81, v81
	v_pk_add_f32 v[84:85], v[84:85], v[86:87]
	v_pk_add_f32 v[78:79], v[78:79], v[82:83]
	s_nop 0
	v_pk_add_f32 v[78:79], v[84:85], v[78:79]
	v_lshl_add_u64 v[84:85], v[136:137], 0, s[0:1]
	v_add_f32_e32 v78, v78, v79
	ds_bpermute_b32 v79, v190, v78
	s_waitcnt lgkmcnt(0)
	v_add_f32_e32 v78, v78, v79
	ds_bpermute_b32 v79, v191, v78
	s_waitcnt lgkmcnt(0)
	v_add_f32_e32 v78, v78, v79
	ds_bpermute_b32 v79, v192, v78
	s_waitcnt lgkmcnt(0)
	v_add_f32_e32 v78, v78, v79
	ds_bpermute_b32 v79, v193, v78
	s_waitcnt lgkmcnt(0)
	v_add_f32_e32 v78, v78, v79
	ds_bpermute_b32 v79, v194, v78
	s_waitcnt lgkmcnt(0)
	v_add_f32_e32 v78, v78, v79
	ds_bpermute_b32 v79, v195, v78
	s_waitcnt lgkmcnt(0)
	v_add_f32_e32 v78, v78, v79
	v_fmamk_f32 v78, v78, 0x3a800000, v197
	v_mul_f32_e32 v79, 0x4b800000, v78
	v_cmp_gt_f32_e32 vcc, s59, v78
	s_nop 1
	v_cndmask_b32_e32 v79, v78, v79, vcc
	v_rsq_f32_e32 v79, v79
	s_nop 0
	v_mul_f32_e32 v82, 0x45800000, v79
	v_cndmask_b32_e32 v82, v79, v82, vcc
	v_pk_mul_f32 v[86:87], v[74:75], v[82:83] op_sel_hi:[1,0]
	v_pk_mul_f32 v[88:89], v[76:77], v[82:83] op_sel_hi:[1,0]
	s_nop 0
	v_cvt_pk_bf16_f32 v88, v88, v89
	v_cvt_pk_bf16_f32 v89, v86, v87
	global_store_dwordx2 v[84:85], v[88:89], off
	v_pk_mul_f32 v[86:87], v[70:71], v[82:83] op_sel_hi:[1,0]
	v_pk_mul_f32 v[88:89], v[72:73], v[82:83] op_sel_hi:[1,0]
	s_nop 0
	v_cvt_pk_bf16_f32 v88, v88, v89
	v_cvt_pk_bf16_f32 v89, v86, v87
	global_store_dwordx2 v[84:85], v[88:89], off offset:512
	v_pk_mul_f32 v[86:87], v[64:65], v[82:83] op_sel_hi:[1,0]
	v_pk_mul_f32 v[88:89], v[66:67], v[82:83] op_sel_hi:[1,0]
	s_nop 0
	v_cvt_pk_bf16_f32 v88, v88, v89
	v_cvt_pk_bf16_f32 v89, v86, v87
	global_store_dwordx2 v[84:85], v[88:89], off offset:1024
	v_pk_mul_f32 v[86:87], v[80:81], v[82:83] op_sel_hi:[1,0]
	v_pk_mul_f32 v[88:89], v[68:69], v[82:83] op_sel_hi:[1,0]
	s_nop 0
	v_cvt_pk_bf16_f32 v88, v88, v89
	v_cvt_pk_bf16_f32 v89, v86, v87
	global_store_dwordx2 v[84:85], v[88:89], off offset:1536
	s_and_saveexec_b64 s[0:1], s[4:5]
	s_cbranch_execz .LBB0_288
	v_mul_f32_e32 v79, 0x4f800000, v78
	v_cmp_gt_f32_e32 vcc, s61, v78
	s_nop 1
	v_cndmask_b32_e32 v78, v78, v79, vcc
	v_sqrt_f32_e32 v79, v78
	s_nop 0
	v_add_u32_e32 v83, -1, v79
	v_fma_f32 v85, -v83, v79, v78
	v_add_u32_e32 v84, 1, v79
	v_cmp_ge_f32_e64 s[10:11], 0, v85
	s_nop 1
	v_cndmask_b32_e64 v83, v79, v83, s[10:11]
	v_fma_f32 v79, -v84, v79, v78
	v_cmp_lt_f32_e64 s[10:11], 0, v79
	s_nop 1
	v_cndmask_b32_e64 v79, v83, v84, s[10:11]
	v_mul_f32_e32 v83, 0x37800000, v79
	s_lshl_b64 s[10:11], s[54:55], 2
	v_cndmask_b32_e32 v79, v79, v83, vcc
	v_cmp_class_f32_e32 vcc, v78, v198
	s_add_u32 s10, s49, s10
	s_addc_u32 s11, s51, s11
	v_cndmask_b32_e32 v78, v79, v78, vcc
	global_store_dword v129, v78, s[10:11]
.LBB0_288:
	s_or_b64 exec, exec, s[0:1]
	ds_read_b128 v[84:87], v235
	ds_read_b128 v[88:91], v230 offset:3072
	ds_read_b128 v[92:95], v230 offset:2048
	ds_read_b128 v[96:99], v230 offset:1024
	ds_read_b128 v[100:103], v230
	v_mul_f32_e32 v76, v76, v82
	v_mul_f32_e32 v74, v74, v82
	v_mul_f32_e32 v72, v72, v82
	v_mul_f32_e32 v70, v70, v82
	v_mul_f32_e32 v66, v66, v82
	v_mul_f32_e32 v64, v64, v82
	v_mul_f32_e32 v68, v68, v82
	v_mul_f32_e32 v80, v80, v82
	s_waitcnt lgkmcnt(4)
	v_mul_f32_e32 v76, v76, v84
	v_mul_f32_e32 v74, v74, v86
	s_waitcnt lgkmcnt(1)
	v_pk_fma_f32 v[98:99], v[98:99], v[76:77], 0 op_sel_hi:[1,0,0]
	s_waitcnt lgkmcnt(0)
	v_pk_fma_f32 v[78:79], v[102:103], v[76:77], 0 op_sel_hi:[1,0,0]
	v_pk_fma_f32 v[100:101], v[100:101], v[76:77], 0 op_sel_hi:[1,0,0]
	v_pk_fma_f32 v[96:97], v[96:97], v[76:77], 0 op_sel_hi:[1,0,0]
	v_mul_f32_e32 v76, v77, v82
	v_mul_f32_e32 v76, v76, v85
	v_pk_fma_f32 v[84:85], v[94:95], v[76:77], v[78:79] op_sel_hi:[1,0,1]
	v_pk_fma_f32 v[100:101], v[92:93], v[76:77], v[100:101] op_sel_hi:[1,0,1]
	v_pk_fma_f32 v[102:103], v[76:77], v[90:91], v[98:99] op_sel_hi:[0,1,1]
	v_pk_fma_f32 v[104:105], v[76:77], v[88:89], v[96:97] op_sel_hi:[0,1,1]
	ds_read_b128 v[76:79], v230 offset:19456
	ds_read_b128 v[88:91], v230 offset:18432
	ds_read_b128 v[92:95], v230 offset:17408
	ds_read_b128 v[96:99], v230 offset:16384
	s_waitcnt lgkmcnt(1)
	v_pk_fma_f32 v[92:93], v[74:75], v[92:93], v[104:105] op_sel_hi:[0,1,1]
	s_waitcnt lgkmcnt(0)
	v_pk_fma_f32 v[96:97], v[74:75], v[96:97], v[100:101] op_sel_hi:[0,1,1]
	v_pk_fma_f32 v[84:85], v[74:75], v[98:99], v[84:85] op_sel_hi:[0,1,1]
	v_pk_fma_f32 v[94:95], v[74:75], v[94:95], v[102:103] op_sel_hi:[0,1,1]
	v_mul_f32_e32 v74, v75, v82
	v_mul_f32_e32 v74, v74, v87
	v_pk_fma_f32 v[100:101], v[74:75], v[90:91], v[84:85] op_sel_hi:[0,1,1]
	v_pk_fma_f32 v[102:103], v[74:75], v[88:89], v[96:97] op_sel_hi:[0,1,1]
	v_pk_fma_f32 v[78:79], v[74:75], v[78:79], v[94:95] op_sel_hi:[0,1,1]
	v_pk_fma_f32 v[104:105], v[74:75], v[76:77], v[92:93] op_sel_hi:[0,1,1]
	ds_read_b128 v[74:77], v235 offset:1024
	ds_read_b128 v[84:87], v230 offset:35840
	ds_read_b128 v[88:91], v230 offset:34816
	ds_read_b128 v[92:95], v230 offset:33792
	ds_read_b128 v[96:99], v230 offset:32768
	s_waitcnt lgkmcnt(4)
	v_mul_f32_e32 v72, v72, v74
	v_mul_f32_e32 v70, v70, v76
	s_waitcnt lgkmcnt(1)
	v_pk_fma_f32 v[92:93], v[92:93], v[72:73], v[104:105] op_sel_hi:[1,0,1]
	s_waitcnt lgkmcnt(0)
	v_pk_fma_f32 v[96:97], v[96:97], v[72:73], v[102:103] op_sel_hi:[1,0,1]
	v_pk_fma_f32 v[98:99], v[98:99], v[72:73], v[100:101] op_sel_hi:[1,0,1]
	v_pk_fma_f32 v[78:79], v[94:95], v[72:73], v[78:79] op_sel_hi:[1,0,1]
	v_mul_f32_e32 v72, v73, v82
	v_mul_f32_e32 v72, v72, v75
	v_pk_fma_f32 v[98:99], v[90:91], v[72:73], v[98:99] op_sel_hi:[1,0,1]
	v_pk_fma_f32 v[96:97], v[88:89], v[72:73], v[96:97] op_sel_hi:[1,0,1]
	v_pk_fma_f32 v[78:79], v[72:73], v[86:87], v[78:79] op_sel_hi:[0,1,1]
	v_pk_fma_f32 v[100:101], v[72:73], v[84:85], v[92:93] op_sel_hi:[0,1,1]
	ds_read_b128 v[72:75], v230 offset:52224
	ds_read_b128 v[84:87], v230 offset:51200
	ds_read_b128 v[88:91], v230 offset:50176
	ds_read_b128 v[92:95], v230 offset:49152
	s_waitcnt lgkmcnt(1)
	v_pk_fma_f32 v[88:89], v[70:71], v[88:89], v[100:101] op_sel_hi:[0,1,1]
	s_waitcnt lgkmcnt(0)
	v_pk_fma_f32 v[92:93], v[70:71], v[92:93], v[96:97] op_sel_hi:[0,1,1]
	v_pk_fma_f32 v[94:95], v[70:71], v[94:95], v[98:99] op_sel_hi:[0,1,1]
	v_pk_fma_f32 v[78:79], v[70:71], v[90:91], v[78:79] op_sel_hi:[0,1,1]
	v_mul_f32_e32 v70, v71, v82
	v_mul_f32_e32 v70, v70, v77
	v_pk_fma_f32 v[96:97], v[70:71], v[86:87], v[94:95] op_sel_hi:[0,1,1]
	v_pk_fma_f32 v[98:99], v[70:71], v[84:85], v[92:93] op_sel_hi:[0,1,1]
	v_pk_fma_f32 v[78:79], v[70:71], v[74:75], v[78:79] op_sel_hi:[0,1,1]
	v_pk_fma_f32 v[100:101], v[70:71], v[72:73], v[88:89] op_sel_hi:[0,1,1]
	ds_read_b128 v[70:73], v235 offset:2048
	ds_read_b128 v[74:77], v231 offset:3072
	ds_read_b128 v[84:87], v231 offset:2048
	ds_read_b128 v[88:91], v231 offset:1024
	ds_read_b128 v[92:95], v231
	s_waitcnt lgkmcnt(4)
	v_mul_f32_e32 v66, v66, v70
	v_mul_f32_e32 v64, v64, v72
	s_waitcnt lgkmcnt(1)
	v_pk_fma_f32 v[88:89], v[88:89], v[66:67], v[100:101] op_sel_hi:[1,0,1]
	s_waitcnt lgkmcnt(0)
	v_pk_fma_f32 v[92:93], v[92:93], v[66:67], v[98:99] op_sel_hi:[1,0,1]
	v_pk_fma_f32 v[94:95], v[94:95], v[66:67], v[96:97] op_sel_hi:[1,0,1]
	v_pk_fma_f32 v[78:79], v[90:91], v[66:67], v[78:79] op_sel_hi:[1,0,1]
	v_mul_f32_e32 v66, v67, v82
	v_mul_f32_e32 v66, v66, v71
	v_pk_fma_f32 v[70:71], v[86:87], v[66:67], v[94:95] op_sel_hi:[1,0,1]
	v_pk_fma_f32 v[96:97], v[84:85], v[66:67], v[92:93] op_sel_hi:[1,0,1]
	v_pk_fma_f32 v[78:79], v[66:67], v[76:77], v[78:79] op_sel_hi:[0,1,1]
	v_pk_fma_f32 v[66:67], v[66:67], v[74:75], v[88:89] op_sel_hi:[0,1,1]
	ds_read_b128 v[74:77], v231 offset:19456
	ds_read_b128 v[84:87], v231 offset:18432
	ds_read_b128 v[88:91], v231 offset:17408
	ds_read_b128 v[92:95], v231 offset:16384
	s_waitcnt lgkmcnt(1)
	v_pk_fma_f32 v[66:67], v[64:65], v[88:89], v[66:67] op_sel_hi:[0,1,1]
	s_waitcnt lgkmcnt(0)
	v_pk_fma_f32 v[92:93], v[64:65], v[92:93], v[96:97] op_sel_hi:[0,1,1]
	v_pk_fma_f32 v[70:71], v[64:65], v[94:95], v[70:71] op_sel_hi:[0,1,1]
	v_pk_fma_f32 v[78:79], v[64:65], v[90:91], v[78:79] op_sel_hi:[0,1,1]
	v_mul_f32_e32 v64, v65, v82
	v_mul_f32_e32 v64, v64, v73
	v_pk_fma_f32 v[94:95], v[64:65], v[86:87], v[70:71] op_sel_hi:[0,1,1]
	v_pk_fma_f32 v[92:93], v[64:65], v[84:85], v[92:93] op_sel_hi:[0,1,1]
	v_pk_fma_f32 v[78:79], v[64:65], v[76:77], v[78:79] op_sel_hi:[0,1,1]
	v_pk_fma_f32 v[96:97], v[64:65], v[74:75], v[66:67] op_sel_hi:[0,1,1]
	ds_read_b128 v[64:67], v235 offset:3072
	ds_read_b128 v[70:73], v231 offset:35840
	ds_read_b128 v[74:77], v231 offset:34816
	ds_read_b128 v[84:87], v231 offset:33792
	ds_read_b128 v[88:91], v231 offset:32768
	s_waitcnt lgkmcnt(4)
	v_mul_f32_e32 v64, v68, v64
	v_mul_f32_e32 v66, v80, v66
	s_waitcnt lgkmcnt(1)
	v_pk_fma_f32 v[84:85], v[84:85], v[64:65], v[96:97] op_sel_hi:[1,0,1]
	s_waitcnt lgkmcnt(0)
	v_pk_fma_f32 v[88:89], v[88:89], v[64:65], v[92:93] op_sel_hi:[1,0,1]
	v_pk_fma_f32 v[90:91], v[90:91], v[64:65], v[94:95] op_sel_hi:[1,0,1]
	v_pk_fma_f32 v[78:79], v[86:87], v[64:65], v[78:79] op_sel_hi:[1,0,1]
	v_mul_f32_e32 v64, v69, v82
	v_mul_f32_e32 v68, v64, v65
	v_pk_fma_f32 v[86:87], v[76:77], v[68:69], v[90:91] op_sel_hi:[1,0,1]
	v_pk_fma_f32 v[88:89], v[74:75], v[68:69], v[88:89] op_sel_hi:[1,0,1]
	v_pk_fma_f32 v[64:65], v[68:69], v[72:73], v[78:79] op_sel_hi:[0,1,1]
	v_pk_fma_f32 v[84:85], v[68:69], v[70:71], v[84:85] op_sel_hi:[0,1,1]
	ds_read_b128 v[68:71], v231 offset:52224
	ds_read_b128 v[72:75], v231 offset:51200
	ds_read_b128 v[76:79], v231 offset:50176
	ds_read_b128 v[90:93], v231 offset:49152
	s_waitcnt lgkmcnt(1)
	v_pk_fma_f32 v[76:77], v[66:67], v[76:77], v[84:85] op_sel_hi:[0,1,1]
	s_waitcnt lgkmcnt(0)
	v_pk_fma_f32 v[88:89], v[66:67], v[90:91], v[88:89] op_sel_hi:[0,1,1]
	v_pk_fma_f32 v[86:87], v[66:67], v[92:93], v[86:87] op_sel_hi:[0,1,1]
	v_pk_fma_f32 v[64:65], v[66:67], v[78:79], v[64:65] op_sel_hi:[0,1,1]
	v_mul_f32_e32 v66, v81, v82
	v_mul_f32_e32 v78, v66, v67
	v_pk_fma_f32 v[64:65], v[78:79], v[70:71], v[64:65] op_sel_hi:[0,1,1]
	v_pk_fma_f32 v[70:71], v[78:79], v[68:69], v[76:77] op_sel_hi:[0,1,1]
	ds_bpermute_b32 v77, v190, v64
	ds_bpermute_b32 v68, v190, v70
	v_pk_fma_f32 v[66:67], v[78:79], v[74:75], v[86:87] op_sel_hi:[0,1,1]
	v_pk_fma_f32 v[72:73], v[78:79], v[72:73], v[88:89] op_sel_hi:[0,1,1]
	ds_bpermute_b32 v74, v190, v72
	s_waitcnt lgkmcnt(2)
	v_add_f32_e32 v64, v64, v77
	ds_bpermute_b32 v77, v191, v64
	s_waitcnt lgkmcnt(2)
	v_add_f32_e32 v68, v70, v68
	ds_bpermute_b32 v75, v190, v73
	ds_bpermute_b32 v70, v190, v71
	ds_bpermute_b32 v76, v190, v66
	s_waitcnt lgkmcnt(3)
	v_add_f32_e32 v64, v64, v77
	ds_bpermute_b32 v77, v192, v64
	s_waitcnt lgkmcnt(3)
	v_pk_add_f32 v[72:73], v[72:73], v[74:75]
	s_waitcnt lgkmcnt(2)
	v_add_f32_e32 v70, v71, v70
	ds_bpermute_b32 v69, v191, v68
	ds_bpermute_b32 v74, v191, v72
	s_waitcnt lgkmcnt(2)
	v_add_f32_e32 v64, v64, v77
	ds_bpermute_b32 v77, v193, v64
	ds_bpermute_b32 v75, v191, v73
	ds_bpermute_b32 v71, v191, v70
	s_waitcnt lgkmcnt(4)
	v_add_f32_e32 v68, v68, v69
	ds_bpermute_b32 v69, v192, v68
	s_waitcnt lgkmcnt(3)
	v_add_f32_e32 v64, v64, v77
	ds_bpermute_b32 v77, v194, v64
	s_waitcnt lgkmcnt(3)
	v_pk_add_f32 v[72:73], v[72:73], v[74:75]
	s_waitcnt lgkmcnt(2)
	v_add_f32_e32 v70, v70, v71
	ds_bpermute_b32 v74, v192, v72
	ds_bpermute_b32 v75, v192, v73
	s_waitcnt lgkmcnt(2)
	v_add_f32_e32 v80, v64, v77
	ds_bpermute_b32 v77, v190, v67
	ds_bpermute_b32 v64, v190, v65
	ds_bpermute_b32 v71, v192, v70
	v_add_f32_e32 v68, v68, v69
	s_waitcnt lgkmcnt(3)
	v_pk_add_f32 v[72:73], v[72:73], v[74:75]
	s_waitcnt lgkmcnt(2)
	v_pk_add_f32 v[66:67], v[66:67], v[76:77]
	s_waitcnt lgkmcnt(1)
	v_add_f32_e32 v64, v65, v64
	ds_bpermute_b32 v76, v191, v66
	ds_bpermute_b32 v77, v191, v67
	ds_bpermute_b32 v65, v191, v64
	s_waitcnt lgkmcnt(3)
	v_add_f32_e32 v70, v70, v71
	ds_bpermute_b32 v69, v193, v68
	ds_bpermute_b32 v74, v193, v72
	s_waitcnt lgkmcnt(3)
	v_pk_add_f32 v[66:67], v[66:67], v[76:77]
	s_waitcnt lgkmcnt(2)
	v_add_f32_e32 v64, v64, v65
	ds_bpermute_b32 v76, v192, v66
	ds_bpermute_b32 v77, v192, v67
	ds_bpermute_b32 v65, v192, v64
	ds_bpermute_b32 v75, v193, v73
	ds_bpermute_b32 v71, v193, v70
	s_waitcnt lgkmcnt(6)
	v_add_f32_e32 v68, v68, v69
	s_waitcnt lgkmcnt(3)
	v_pk_add_f32 v[66:67], v[66:67], v[76:77]
	s_waitcnt lgkmcnt(2)
	v_add_f32_e32 v64, v64, v65
	ds_bpermute_b32 v76, v193, v66
	ds_bpermute_b32 v77, v193, v67
	ds_bpermute_b32 v65, v193, v64
	s_waitcnt lgkmcnt(4)
	v_pk_add_f32 v[72:73], v[72:73], v[74:75]
	s_waitcnt lgkmcnt(3)
	v_add_f32_e32 v70, v70, v71
	ds_bpermute_b32 v69, v194, v68
	s_waitcnt lgkmcnt(2)
	v_pk_add_f32 v[66:67], v[66:67], v[76:77]
	s_waitcnt lgkmcnt(1)
	v_add_f32_e32 v64, v64, v65
	ds_bpermute_b32 v74, v194, v72
	ds_bpermute_b32 v75, v194, v73
	ds_bpermute_b32 v71, v194, v70
	ds_bpermute_b32 v76, v194, v66
	ds_bpermute_b32 v77, v194, v67
	ds_bpermute_b32 v65, v194, v64
	s_waitcnt lgkmcnt(6)
	v_add_f32_e32 v68, v68, v69
	s_waitcnt lgkmcnt(4)
	v_pk_add_f32 v[72:73], v[72:73], v[74:75]
	s_waitcnt lgkmcnt(3)
	v_add_f32_e32 v70, v70, v71
	s_waitcnt lgkmcnt(1)
	v_pk_add_f32 v[76:77], v[66:67], v[76:77]
	s_waitcnt lgkmcnt(0)
	v_add_f32_e32 v82, v64, v65
	ds_bpermute_b32 v69, v195, v68
	ds_bpermute_b32 v74, v195, v72
	ds_bpermute_b32 v75, v195, v73
	ds_bpermute_b32 v71, v195, v70
	ds_bpermute_b32 v81, v195, v80
	ds_bpermute_b32 v78, v195, v76
	ds_bpermute_b32 v79, v195, v77
	ds_bpermute_b32 v83, v195, v82
	s_and_saveexec_b64 s[0:1], 15
	s_cbranch_execz .LBB0_261
	s_waitcnt lgkmcnt(0)
	v_add_f32_e32 v120, v82, v83
	v_add_f32_e32 v82, v68, v69
	v_add_f32_e32 v83, v70, v71
	v_add_f32_e32 v121, v80, v81
	v_mov_b64_e32 v[80:81], s[44:45]
	v_pk_add_f32 v[72:73], v[72:73], v[74:75]
	v_pk_add_f32 v[76:77], v[76:77], v[78:79]
	s_lshl_b64 s[10:11], s[54:55], 5
	s_add_u32 s10, s53, s10
	s_addc_u32 s11, s58, s11
	v_mov_b32_e32 v64, v82
	v_mov_b32_e32 v65, v72
	s_mov_b64 vcc, 2
	v_cndmask_b32_e32 v64, v64, v83, vcc
	v_cndmask_b32_e32 v65, v65, v73, vcc
	s_mov_b64 vcc, 4
	v_cndmask_b32_e32 v64, v64, v121, vcc
	v_cndmask_b32_e32 v65, v65, v76, vcc
	s_mov_b64 vcc, 8
	v_cndmask_b32_e32 v64, v64, v120, vcc
	v_cndmask_b32_e32 v65, v65, v77, vcc
	v_add_f32_e32 v64, v64, v236
	v_add_f32_e32 v65, v65, v237
	global_store_dword v232, v65, s[10:11]
	s_nop 0
	v_mul_f32_e64 v82, |v64|, s62
	s_nop 0
	v_exp_f32_e32 v122, v82
	s_nop 0
	v_add_f32_e32 v86, 1.0, v122
	s_nop 0
	v_frexp_mant_f32_e32 v89, v86
	v_cvt_f64_f32_e32 v[82:83], v86
	s_nop 0
	v_frexp_exp_i32_f64_e32 v82, v[82:83]
	v_cmp_gt_f32_e32 vcc, s63, v89
	v_add_f32_e32 v88, -1.0, v86
	s_nop 0
	v_subbrev_co_u32_e32 v82, vcc, 0, v82, vcc
	v_sub_f32_e32 v92, v88, v86
	v_sub_f32_e32 v88, v122, v88
	v_add_f32_e32 v85, 1.0, v92
	s_nop 0
	v_add_f32_e32 v85, v88, v85
	v_sub_u32_e32 v88, 0, v82
	v_cvt_f32_i32_e32 v82, v82
	v_ldexp_f32 v84, v86, v88
	v_ldexp_f32 v86, v85, v88
	v_add_f32_e32 v88, 1.0, v84
	v_add_f32_e32 v90, -1.0, v84
	v_add_f32_e32 v92, -1.0, v88
	v_add_f32_e32 v94, 1.0, v90
	v_sub_f32_e32 v92, v84, v92
	v_sub_f32_e32 v84, v84, v94
	v_mul_f32_e32 v94, s50, v82
	v_add_f32_e32 v92, v86, v92
	v_add_f32_e32 v84, v86, v84
	v_fma_f32 v86, v82, s50, -v94
	v_add_f32_e32 v100, v88, v92
	v_fma_f32 v82, v82, s52, v86
	v_rcp_f32_e32 v86, v100
	v_add_f32_e32 v102, v90, v84
	v_sub_f32_e32 v88, v100, v88
	v_sub_f32_e32 v90, v102, v90
	v_mul_f32_e32 v110, v102, v86
	v_sub_f32_e32 v88, v92, v88
	v_mul_f32_e32 v112, v100, v110
	v_sub_f32_e32 v84, v84, v90
	v_fma_f32 v114, v110, v100, -v112
	v_add_f32_e32 v104, v94, v82
	v_fma_f32 v114, v110, v88, v114
	v_mov_b32_e32 v96, v94
	v_add_f32_e32 v116, v112, v114
	v_mov_b32_e32 v106, v82
	v_sub_f32_e32 v118, v102, v116
	v_sub_f32_e32 v112, v116, v112
	v_sub_f32_e32 v102, v102, v118
	v_sub_f32_e32 v112, v112, v114
	v_sub_f32_e32 v102, v102, v116
	s_nop 0
	v_add_f32_e32 v84, v84, v102
	s_nop 0
	v_add_f32_e32 v84, v112, v84
	s_nop 0
	v_add_f32_e32 v102, v118, v84
	v_mov_b32_e32 v98, v104
	v_mul_f32_e32 v112, v86, v102
	v_sub_f32_e32 v114, v118, v102
	v_mul_f32_e32 v116, v100, v112
	v_add_f32_e32 v84, v84, v114
	v_add_f32_e32 v114, v110, v112
	v_fma_f32 v100, v112, v100, -v116
	v_sub_f32_e32 v110, v114, v110
	v_fma_f32 v88, v112, v88, v100
	v_sub_f32_e32 v100, v112, v110
	v_add_f32_e32 v110, v116, v88
	s_nop 0
	v_sub_f32_e32 v112, v110, v116
	v_sub_f32_e32 v116, v102, v110
	v_sub_f32_e32 v88, v112, v88
	v_sub_f32_e32 v102, v102, v116
	v_cmp_neq_f32_e32 vcc, s64, v122
	v_sub_f32_e32 v102, v102, v110
	s_nop 0
	v_add_f32_e32 v84, v84, v102
	s_nop 0
	v_add_f32_e32 v84, v88, v84
	v_min_f32_e32 v64, 0, v64
	v_add_f32_e32 v84, v116, v84
	s_nop 0
	v_mul_f32_e32 v84, v86, v84
	s_nop 0
	v_add_f32_e32 v84, v100, v84
	s_nop 0
	v_add_f32_e32 v86, v114, v84
	s_nop 0
	v_sub_f32_e32 v88, v86, v114
	v_mul_f32_e32 v102, v86, v86
	v_sub_f32_e32 v84, v84, v88
	v_fma_f32 v88, v102, s46, v80
	v_ldexp_f32 v100, v86, 1
	v_mul_f32_e32 v86, v86, v102
	v_fma_f32 v88, v102, v88, s48
	s_nop 0
	v_mul_f32_e32 v86, v86, v88
	v_ldexp_f32 v84, v84, 1
	v_add_f32_e32 v88, v100, v86
	s_nop 0
	v_sub_f32_e32 v100, v88, v100
	v_mov_b32_e32 v92, v88
	v_sub_f32_e32 v86, v86, v100
	s_nop 0
	v_add_f32_e32 v100, v84, v86
	s_nop 0
	v_add_f32_e32 v102, v88, v100
	v_add_f32_e32 v84, v84, v86
	v_add_f32_e32 v86, v104, v102
	v_add_f32_e32 v96, v96, v106
	v_mov_b32_e32 v106, v102
	s_nop 0
	v_sub_f32_e32 v92, v106, v92
	v_mov_b32_e32 v90, v86
	v_mov_b32_e32 v106, v104
	v_mov_b32_e32 v108, v102
	v_sub_f32_e32 v90, v90, v98
	v_sub_f32_e32 v94, v106, v94
	v_sub_f32_e32 v98, v108, v90
	v_mov_b32_e32 v106, v94
	v_mov_b32_e32 v108, v86
	v_sub_f32_e32 v106, v82, v106
	v_sub_f32_e32 v90, v108, v90
	s_nop 0
	v_sub_f32_e32 v90, v96, v90
	v_sub_f32_e32 v82, v82, v94
	v_sub_f32_e32 v84, v84, v92
	v_add_f32_e32 v94, v98, v90
	v_add_f32_e32 v92, v84, v82
	v_add_f32_e32 v84, v82, v84
	v_sub_f32_e32 v88, v102, v88
	v_sub_f32_e32 v84, v84, v106
	v_mov_b32_e32 v90, v92
	v_sub_f32_e32 v88, v100, v88
	v_sub_f32_e32 v90, v90, v84
	v_sub_f32_e32 v84, v88, v84
	v_sub_f32_e32 v82, v82, v90
	s_nop 0
	v_add_f32_e32 v82, v84, v82
	v_add_f32_e32 v84, v94, v92
	s_nop 0
	v_add_f32_e32 v88, v86, v84
	s_nop 0
	v_sub_f32_e32 v86, v88, v86
	s_nop 0
	v_sub_f32_e32 v84, v84, v86
	s_nop 0
	v_add_f32_e32 v82, v82, v84
	s_nop 0
	v_add_f32_e32 v82, v88, v82
	s_nop 0
	v_cndmask_b32_e32 v82, v200, v82, vcc
	v_cmp_ngt_f32_e32 vcc, -1.0, v122
	s_nop 1
	v_cndmask_b32_e32 v82, v201, v82, vcc
	v_cmp_neq_f32_e32 vcc, -1.0, v122
	s_nop 1
	v_cndmask_b32_e32 v82, v202, v82, vcc
	v_cmp_lt_f32_e64 vcc, |v122|, s65
	s_nop 1
	v_cndmask_b32_e32 v82, v82, v122, vcc
	s_nop 0
	v_sub_f32_e32 v64, v64, v82
	s_nop 0
	global_store_dword v232, v64, s[10:11] offset:16
	s_branch .LBB0_261
